# P7 rope-part epilogue rewritten by hand (table loads 4 groups ahead, merged 16-byte stores); P13 gate epilogue stores full 128-byte lines (half-row exchange by DPP)
# speedup vs baseline: 1.1394x; 1.0016x over previous
.LBB0_1143:
	s_andn2_b64 vcc, exec, s[0:1]
	s_cbranch_vccnz .LBB0_1002
	v_and_b32_e32 v156, 15, v198
	v_lshrrev_b32_e32 v157, 8, v198
	v_lshl_add_u32 v156, v157, 6, v156
	v_bfe_u32 v157, v198, 4, 2
	v_bfe_u32 v158, v198, 6, 2
	s_cmp_lt_u32 s40, 64
	s_cselect_b64 s[10:11], -1, 0
	s_cselect_b32 s8, -1, 0
	s_and_b32 s9, s40, 15
	s_lshl_b32 s9, s9, 8
	v_add_u32_e32 v159, s9, v156
	v_and_b32_e32 v151, 7, v198
	v_or_b32_e32 v151, 0x1000, v151
	v_cndmask_b32_e64 v151, v151, v159, s[10:11]
	v_lshlrev_b32_e32 v151, 10, v151
	v_lshl_add_u32 v151, v158, 8, v151
	v_lshl_add_u32 v151, v157, 5, v151
	s_lshl_b32 s9, s40, 8
	v_add_u32_e32 v152, s9, v156
	v_lshlrev_b32_e32 v152, 11, v152
	v_lshl_add_u32 v152, v158, 6, v152
	v_lshl_add_u32 v152, v157, 3, v152
	v_and_b32_e32 v159, 1, v157
	v_mul_u32_u24_e32 v159, 24, v159
	v_add_u32_e32 v152, v152, v159
	s_add_u32 s60, s94, 0x1d00800
	s_addc_u32 s61, s95, 0
	s_cmp_lt_u32 s38, 4
	s_mov_b32 s9, 0x1a802800
	s_mov_b32 s14, 0x1ca02800
	s_cselect_b32 s9, s9, s14
	s_mov_b32 s14, 0x3d800000
	s_cselect_b32 s14, 1.0, s14
	s_and_b32 s33, s38, 3
	s_lshl_b32 s33, s33, 9
	s_add_u32 s9, s9, s33
	s_add_u32 s62, s94, s9
	s_addc_u32 s63, s95, 0
	v_mov_b32_e32 v154, s14
	v_mov_b32_e32 v155, s14
	global_load_dwordx4 v[200:203], v151, s[60:61]
	global_load_dwordx4 v[204:207], v151, s[60:61] offset:16
	global_load_dwordx4 v[208:211], v151, s[60:61] offset:128
	global_load_dwordx4 v[212:215], v151, s[60:61] offset:144
	s_and_b32 s33, s8, 0x4000
	s_add_u32 s64, s60, s33
	s_addc_u32 s65, s61, 0
	global_load_dwordx4 v[216:219], v151, s[64:65]
	global_load_dwordx4 v[220:223], v151, s[64:65] offset:16
	global_load_dwordx4 v[224:227], v151, s[64:65] offset:128
	global_load_dwordx4 v[228:231], v151, s[64:65] offset:144
	s_and_b32 s33, s8, 0x8000
	s_add_u32 s64, s60, s33
	s_addc_u32 s65, s61, 0
	global_load_dwordx4 v[232:235], v151, s[64:65]
	global_load_dwordx4 v[236:239], v151, s[64:65] offset:16
	global_load_dwordx4 v[240:243], v151, s[64:65] offset:128
	global_load_dwordx4 v[244:247], v151, s[64:65] offset:144
	s_and_b32 s33, s8, 0xc000
	s_add_u32 s64, s60, s33
	s_addc_u32 s65, s61, 0
	global_load_dwordx4 v[170:173], v151, s[64:65]
	global_load_dwordx4 v[174:177], v151, s[64:65] offset:16
	global_load_dwordx4 v[178:181], v151, s[64:65] offset:128
	global_load_dwordx4 v[182:185], v151, s[64:65] offset:144
	s_waitcnt vmcnt(12)
	v_swap_b32_e32 v201, v202
	v_swap_b32_e32 v205, v206
	v_swap_b32_e32 v209, v210
	v_swap_b32_e32 v213, v214
	v_pk_mul_f32 v[186:187], v[120:121], v[202:203]
	v_pk_mul_f32 v[188:189], v[124:125], v[202:203]
	v_pk_fma_f32 v[124:125], v[124:125], v[200:201], v[186:187] neg_lo:[0,0,1] neg_hi:[0,0,1]
	v_pk_fma_f32 v[120:121], v[120:121], v[200:201], v[188:189]
	v_pk_mul_f32 v[124:125], v[124:125], v[154:155]
	v_pk_mul_f32 v[120:121], v[120:121], v[154:155]
	v_pk_mul_f32 v[186:187], v[122:123], v[206:207]
	v_pk_mul_f32 v[188:189], v[126:127], v[206:207]
	v_pk_fma_f32 v[126:127], v[126:127], v[204:205], v[186:187] neg_lo:[0,0,1] neg_hi:[0,0,1]
	v_pk_fma_f32 v[122:123], v[122:123], v[204:205], v[188:189]
	v_pk_mul_f32 v[126:127], v[126:127], v[154:155]
	v_pk_mul_f32 v[122:123], v[122:123], v[154:155]
	v_pk_mul_f32 v[186:187], v[112:113], v[210:211]
	v_pk_mul_f32 v[188:189], v[116:117], v[210:211]
	v_pk_fma_f32 v[116:117], v[116:117], v[208:209], v[186:187] neg_lo:[0,0,1] neg_hi:[0,0,1]
	v_pk_fma_f32 v[112:113], v[112:113], v[208:209], v[188:189]
	v_pk_mul_f32 v[116:117], v[116:117], v[154:155]
	v_pk_mul_f32 v[112:113], v[112:113], v[154:155]
	v_pk_mul_f32 v[186:187], v[114:115], v[214:215]
	v_pk_mul_f32 v[188:189], v[118:119], v[214:215]
	v_pk_fma_f32 v[118:119], v[118:119], v[212:213], v[186:187] neg_lo:[0,0,1] neg_hi:[0,0,1]
	v_pk_fma_f32 v[114:115], v[114:115], v[212:213], v[188:189]
	v_pk_mul_f32 v[118:119], v[118:119], v[154:155]
	v_pk_mul_f32 v[114:115], v[114:115], v[154:155]
	v_cvt_pk_bf16_f32 v190, v124, v125
	v_cvt_pk_bf16_f32 v191, v126, v127
	v_cvt_pk_bf16_f32 v192, v116, v117
	v_cvt_pk_bf16_f32 v193, v118, v119
	v_cvt_pk_bf16_f32 v194, v120, v121
	v_cvt_pk_bf16_f32 v195, v122, v123
	v_cvt_pk_bf16_f32 v196, v112, v113
	v_cvt_pk_bf16_f32 v197, v114, v115
	v_permlane16_swap_b32_e32 v190, v192
	v_permlane16_swap_b32_e32 v191, v193
	v_permlane16_swap_b32_e32 v194, v196
	v_permlane16_swap_b32_e32 v195, v197
	global_store_dwordx4 v152, v[190:193], s[62:63]
	global_store_dwordx4 v152, v[194:197], s[62:63] offset:256
	s_and_b32 s33, s8, 0x20000
	s_add_u32 s64, s60, s33
	s_addc_u32 s65, s61, 0
	global_load_dwordx4 v[200:203], v151, s[64:65]
	global_load_dwordx4 v[204:207], v151, s[64:65] offset:16
	global_load_dwordx4 v[208:211], v151, s[64:65] offset:128
	global_load_dwordx4 v[212:215], v151, s[64:65] offset:144
	s_waitcnt vmcnt(14)
	v_swap_b32_e32 v217, v218
	v_swap_b32_e32 v221, v222
	v_swap_b32_e32 v225, v226
	v_swap_b32_e32 v229, v230
	v_pk_mul_f32 v[186:187], v[104:105], v[218:219]
	v_pk_mul_f32 v[188:189], v[108:109], v[218:219]
	v_pk_fma_f32 v[108:109], v[108:109], v[216:217], v[186:187] neg_lo:[0,0,1] neg_hi:[0,0,1]
	v_pk_fma_f32 v[104:105], v[104:105], v[216:217], v[188:189]
	v_pk_mul_f32 v[108:109], v[108:109], v[154:155]
	v_pk_mul_f32 v[104:105], v[104:105], v[154:155]
	v_pk_mul_f32 v[186:187], v[106:107], v[222:223]
	v_pk_mul_f32 v[188:189], v[110:111], v[222:223]
	v_pk_fma_f32 v[110:111], v[110:111], v[220:221], v[186:187] neg_lo:[0,0,1] neg_hi:[0,0,1]
	v_pk_fma_f32 v[106:107], v[106:107], v[220:221], v[188:189]
	v_pk_mul_f32 v[110:111], v[110:111], v[154:155]
	v_pk_mul_f32 v[106:107], v[106:107], v[154:155]
	v_pk_mul_f32 v[186:187], v[96:97], v[226:227]
	v_pk_mul_f32 v[188:189], v[100:101], v[226:227]
	v_pk_fma_f32 v[100:101], v[100:101], v[224:225], v[186:187] neg_lo:[0,0,1] neg_hi:[0,0,1]
	v_pk_fma_f32 v[96:97], v[96:97], v[224:225], v[188:189]
	v_pk_mul_f32 v[100:101], v[100:101], v[154:155]
	v_pk_mul_f32 v[96:97], v[96:97], v[154:155]
	v_pk_mul_f32 v[186:187], v[98:99], v[230:231]
	v_pk_mul_f32 v[188:189], v[102:103], v[230:231]
	v_pk_fma_f32 v[102:103], v[102:103], v[228:229], v[186:187] neg_lo:[0,0,1] neg_hi:[0,0,1]
	v_pk_fma_f32 v[98:99], v[98:99], v[228:229], v[188:189]
	v_pk_mul_f32 v[102:103], v[102:103], v[154:155]
	v_pk_mul_f32 v[98:99], v[98:99], v[154:155]
	v_cvt_pk_bf16_f32 v190, v108, v109
	v_cvt_pk_bf16_f32 v191, v110, v111
	v_cvt_pk_bf16_f32 v192, v100, v101
	v_cvt_pk_bf16_f32 v193, v102, v103
	v_cvt_pk_bf16_f32 v194, v104, v105
	v_cvt_pk_bf16_f32 v195, v106, v107
	v_cvt_pk_bf16_f32 v196, v96, v97
	v_cvt_pk_bf16_f32 v197, v98, v99
	v_permlane16_swap_b32_e32 v190, v192
	v_permlane16_swap_b32_e32 v191, v193
	v_permlane16_swap_b32_e32 v194, v196
	v_permlane16_swap_b32_e32 v195, v197
	s_add_u32 s66, s62, 0x8000
	s_addc_u32 s67, s63, 0
	global_store_dwordx4 v152, v[190:193], s[66:67]
	global_store_dwordx4 v152, v[194:197], s[66:67] offset:256
	s_and_b32 s33, s8, 0x24000
	s_add_u32 s64, s60, s33
	s_addc_u32 s65, s61, 0
	global_load_dwordx4 v[216:219], v151, s[64:65]
	global_load_dwordx4 v[220:223], v151, s[64:65] offset:16
	global_load_dwordx4 v[224:227], v151, s[64:65] offset:128
	global_load_dwordx4 v[228:231], v151, s[64:65] offset:144
	s_waitcnt vmcnt(16)
	v_swap_b32_e32 v233, v234
	v_swap_b32_e32 v237, v238
	v_swap_b32_e32 v241, v242
	v_swap_b32_e32 v245, v246
	v_pk_mul_f32 v[186:187], v[88:89], v[234:235]
	v_pk_mul_f32 v[188:189], v[92:93], v[234:235]
	v_pk_fma_f32 v[92:93], v[92:93], v[232:233], v[186:187] neg_lo:[0,0,1] neg_hi:[0,0,1]
	v_pk_fma_f32 v[88:89], v[88:89], v[232:233], v[188:189]
	v_pk_mul_f32 v[92:93], v[92:93], v[154:155]
	v_pk_mul_f32 v[88:89], v[88:89], v[154:155]
	v_pk_mul_f32 v[186:187], v[90:91], v[238:239]
	v_pk_mul_f32 v[188:189], v[94:95], v[238:239]
	v_pk_fma_f32 v[94:95], v[94:95], v[236:237], v[186:187] neg_lo:[0,0,1] neg_hi:[0,0,1]
	v_pk_fma_f32 v[90:91], v[90:91], v[236:237], v[188:189]
	v_pk_mul_f32 v[94:95], v[94:95], v[154:155]
	v_pk_mul_f32 v[90:91], v[90:91], v[154:155]
	v_pk_mul_f32 v[186:187], v[80:81], v[242:243]
	v_pk_mul_f32 v[188:189], v[84:85], v[242:243]
	v_pk_fma_f32 v[84:85], v[84:85], v[240:241], v[186:187] neg_lo:[0,0,1] neg_hi:[0,0,1]
	v_pk_fma_f32 v[80:81], v[80:81], v[240:241], v[188:189]
	v_pk_mul_f32 v[84:85], v[84:85], v[154:155]
	v_pk_mul_f32 v[80:81], v[80:81], v[154:155]
	v_pk_mul_f32 v[186:187], v[82:83], v[246:247]
	v_pk_mul_f32 v[188:189], v[86:87], v[246:247]
	v_pk_fma_f32 v[86:87], v[86:87], v[244:245], v[186:187] neg_lo:[0,0,1] neg_hi:[0,0,1]
	v_pk_fma_f32 v[82:83], v[82:83], v[244:245], v[188:189]
	v_pk_mul_f32 v[86:87], v[86:87], v[154:155]
	v_pk_mul_f32 v[82:83], v[82:83], v[154:155]
	v_cvt_pk_bf16_f32 v190, v92, v93
	v_cvt_pk_bf16_f32 v191, v94, v95
	v_cvt_pk_bf16_f32 v192, v84, v85
	v_cvt_pk_bf16_f32 v193, v86, v87
	v_cvt_pk_bf16_f32 v194, v88, v89
	v_cvt_pk_bf16_f32 v195, v90, v91
	v_cvt_pk_bf16_f32 v196, v80, v81
	v_cvt_pk_bf16_f32 v197, v82, v83
	v_permlane16_swap_b32_e32 v190, v192
	v_permlane16_swap_b32_e32 v191, v193
	v_permlane16_swap_b32_e32 v194, v196
	v_permlane16_swap_b32_e32 v195, v197
	s_add_u32 s66, s62, 0x10000
	s_addc_u32 s67, s63, 0
	global_store_dwordx4 v152, v[190:193], s[66:67]
	global_store_dwordx4 v152, v[194:197], s[66:67] offset:256
	s_and_b32 s33, s8, 0x28000
	s_add_u32 s64, s60, s33
	s_addc_u32 s65, s61, 0
	global_load_dwordx4 v[232:235], v151, s[64:65]
	global_load_dwordx4 v[236:239], v151, s[64:65] offset:16
	global_load_dwordx4 v[240:243], v151, s[64:65] offset:128
	global_load_dwordx4 v[244:247], v151, s[64:65] offset:144
	s_waitcnt vmcnt(18)
	v_swap_b32_e32 v171, v172
	v_swap_b32_e32 v175, v176
	v_swap_b32_e32 v179, v180
	v_swap_b32_e32 v183, v184
	v_pk_mul_f32 v[186:187], v[72:73], v[172:173]
	v_pk_mul_f32 v[188:189], v[76:77], v[172:173]
	v_pk_fma_f32 v[76:77], v[76:77], v[170:171], v[186:187] neg_lo:[0,0,1] neg_hi:[0,0,1]
	v_pk_fma_f32 v[72:73], v[72:73], v[170:171], v[188:189]
	v_pk_mul_f32 v[76:77], v[76:77], v[154:155]
	v_pk_mul_f32 v[72:73], v[72:73], v[154:155]
	v_pk_mul_f32 v[186:187], v[74:75], v[176:177]
	v_pk_mul_f32 v[188:189], v[78:79], v[176:177]
	v_pk_fma_f32 v[78:79], v[78:79], v[174:175], v[186:187] neg_lo:[0,0,1] neg_hi:[0,0,1]
	v_pk_fma_f32 v[74:75], v[74:75], v[174:175], v[188:189]
	v_pk_mul_f32 v[78:79], v[78:79], v[154:155]
	v_pk_mul_f32 v[74:75], v[74:75], v[154:155]
	v_pk_mul_f32 v[186:187], v[64:65], v[180:181]
	v_pk_mul_f32 v[188:189], v[68:69], v[180:181]
	v_pk_fma_f32 v[68:69], v[68:69], v[178:179], v[186:187] neg_lo:[0,0,1] neg_hi:[0,0,1]
	v_pk_fma_f32 v[64:65], v[64:65], v[178:179], v[188:189]
	v_pk_mul_f32 v[68:69], v[68:69], v[154:155]
	v_pk_mul_f32 v[64:65], v[64:65], v[154:155]
	v_pk_mul_f32 v[186:187], v[66:67], v[184:185]
	v_pk_mul_f32 v[188:189], v[70:71], v[184:185]
	v_pk_fma_f32 v[70:71], v[70:71], v[182:183], v[186:187] neg_lo:[0,0,1] neg_hi:[0,0,1]
	v_pk_fma_f32 v[66:67], v[66:67], v[182:183], v[188:189]
	v_pk_mul_f32 v[70:71], v[70:71], v[154:155]
	v_pk_mul_f32 v[66:67], v[66:67], v[154:155]
	v_cvt_pk_bf16_f32 v190, v76, v77
	v_cvt_pk_bf16_f32 v191, v78, v79
	v_cvt_pk_bf16_f32 v192, v68, v69
	v_cvt_pk_bf16_f32 v193, v70, v71
	v_cvt_pk_bf16_f32 v194, v72, v73
	v_cvt_pk_bf16_f32 v195, v74, v75
	v_cvt_pk_bf16_f32 v196, v64, v65
	v_cvt_pk_bf16_f32 v197, v66, v67
	v_permlane16_swap_b32_e32 v190, v192
	v_permlane16_swap_b32_e32 v191, v193
	v_permlane16_swap_b32_e32 v194, v196
	v_permlane16_swap_b32_e32 v195, v197
	s_add_u32 s66, s62, 0x18000
	s_addc_u32 s67, s63, 0
	global_store_dwordx4 v152, v[190:193], s[66:67]
	global_store_dwordx4 v152, v[194:197], s[66:67] offset:256
	s_and_b32 s33, s8, 0x2c000
	s_add_u32 s64, s60, s33
	s_addc_u32 s65, s61, 0
	global_load_dwordx4 v[170:173], v151, s[64:65]
	global_load_dwordx4 v[174:177], v151, s[64:65] offset:16
	global_load_dwordx4 v[178:181], v151, s[64:65] offset:128
	global_load_dwordx4 v[182:185], v151, s[64:65] offset:144
	s_waitcnt vmcnt(18)
	v_swap_b32_e32 v201, v202
	v_swap_b32_e32 v205, v206
	v_swap_b32_e32 v209, v210
	v_swap_b32_e32 v213, v214
	v_pk_mul_f32 v[186:187], v[56:57], v[202:203]
	v_pk_mul_f32 v[188:189], v[60:61], v[202:203]
	v_pk_fma_f32 v[60:61], v[60:61], v[200:201], v[186:187] neg_lo:[0,0,1] neg_hi:[0,0,1]
	v_pk_fma_f32 v[56:57], v[56:57], v[200:201], v[188:189]
	v_pk_mul_f32 v[60:61], v[60:61], v[154:155]
	v_pk_mul_f32 v[56:57], v[56:57], v[154:155]
	v_pk_mul_f32 v[186:187], v[58:59], v[206:207]
	v_pk_mul_f32 v[188:189], v[62:63], v[206:207]
	v_pk_fma_f32 v[62:63], v[62:63], v[204:205], v[186:187] neg_lo:[0,0,1] neg_hi:[0,0,1]
	v_pk_fma_f32 v[58:59], v[58:59], v[204:205], v[188:189]
	v_pk_mul_f32 v[62:63], v[62:63], v[154:155]
	v_pk_mul_f32 v[58:59], v[58:59], v[154:155]
	v_pk_mul_f32 v[186:187], v[48:49], v[210:211]
	v_pk_mul_f32 v[188:189], v[52:53], v[210:211]
	v_pk_fma_f32 v[52:53], v[52:53], v[208:209], v[186:187] neg_lo:[0,0,1] neg_hi:[0,0,1]
	v_pk_fma_f32 v[48:49], v[48:49], v[208:209], v[188:189]
	v_pk_mul_f32 v[52:53], v[52:53], v[154:155]
	v_pk_mul_f32 v[48:49], v[48:49], v[154:155]
	v_pk_mul_f32 v[186:187], v[50:51], v[214:215]
	v_pk_mul_f32 v[188:189], v[54:55], v[214:215]
	v_pk_fma_f32 v[54:55], v[54:55], v[212:213], v[186:187] neg_lo:[0,0,1] neg_hi:[0,0,1]
	v_pk_fma_f32 v[50:51], v[50:51], v[212:213], v[188:189]
	v_pk_mul_f32 v[54:55], v[54:55], v[154:155]
	v_pk_mul_f32 v[50:51], v[50:51], v[154:155]
	v_cvt_pk_bf16_f32 v190, v60, v61
	v_cvt_pk_bf16_f32 v191, v62, v63
	v_cvt_pk_bf16_f32 v192, v52, v53
	v_cvt_pk_bf16_f32 v193, v54, v55
	v_cvt_pk_bf16_f32 v194, v56, v57
	v_cvt_pk_bf16_f32 v195, v58, v59
	v_cvt_pk_bf16_f32 v196, v48, v49
	v_cvt_pk_bf16_f32 v197, v50, v51
	v_permlane16_swap_b32_e32 v190, v192
	v_permlane16_swap_b32_e32 v191, v193
	v_permlane16_swap_b32_e32 v194, v196
	v_permlane16_swap_b32_e32 v195, v197
	s_add_u32 s66, s62, 0x40000
	s_addc_u32 s67, s63, 0
	global_store_dwordx4 v152, v[190:193], s[66:67]
	global_store_dwordx4 v152, v[194:197], s[66:67] offset:256
	s_waitcnt vmcnt(14)
	v_swap_b32_e32 v217, v218
	v_swap_b32_e32 v221, v222
	v_swap_b32_e32 v225, v226
	v_swap_b32_e32 v229, v230
	v_pk_mul_f32 v[186:187], v[40:41], v[218:219]
	v_pk_mul_f32 v[188:189], v[44:45], v[218:219]
	v_pk_fma_f32 v[44:45], v[44:45], v[216:217], v[186:187] neg_lo:[0,0,1] neg_hi:[0,0,1]
	v_pk_fma_f32 v[40:41], v[40:41], v[216:217], v[188:189]
	v_pk_mul_f32 v[44:45], v[44:45], v[154:155]
	v_pk_mul_f32 v[40:41], v[40:41], v[154:155]
	v_pk_mul_f32 v[186:187], v[42:43], v[222:223]
	v_pk_mul_f32 v[188:189], v[46:47], v[222:223]
	v_pk_fma_f32 v[46:47], v[46:47], v[220:221], v[186:187] neg_lo:[0,0,1] neg_hi:[0,0,1]
	v_pk_fma_f32 v[42:43], v[42:43], v[220:221], v[188:189]
	v_pk_mul_f32 v[46:47], v[46:47], v[154:155]
	v_pk_mul_f32 v[42:43], v[42:43], v[154:155]
	v_pk_mul_f32 v[186:187], v[32:33], v[226:227]
	v_pk_mul_f32 v[188:189], v[36:37], v[226:227]
	v_pk_fma_f32 v[36:37], v[36:37], v[224:225], v[186:187] neg_lo:[0,0,1] neg_hi:[0,0,1]
	v_pk_fma_f32 v[32:33], v[32:33], v[224:225], v[188:189]
	v_pk_mul_f32 v[36:37], v[36:37], v[154:155]
	v_pk_mul_f32 v[32:33], v[32:33], v[154:155]
	v_pk_mul_f32 v[186:187], v[34:35], v[230:231]
	v_pk_mul_f32 v[188:189], v[38:39], v[230:231]
	v_pk_fma_f32 v[38:39], v[38:39], v[228:229], v[186:187] neg_lo:[0,0,1] neg_hi:[0,0,1]
	v_pk_fma_f32 v[34:35], v[34:35], v[228:229], v[188:189]
	v_pk_mul_f32 v[38:39], v[38:39], v[154:155]
	v_pk_mul_f32 v[34:35], v[34:35], v[154:155]
	v_cvt_pk_bf16_f32 v190, v44, v45
	v_cvt_pk_bf16_f32 v191, v46, v47
	v_cvt_pk_bf16_f32 v192, v36, v37
	v_cvt_pk_bf16_f32 v193, v38, v39
	v_cvt_pk_bf16_f32 v194, v40, v41
	v_cvt_pk_bf16_f32 v195, v42, v43
	v_cvt_pk_bf16_f32 v196, v32, v33
	v_cvt_pk_bf16_f32 v197, v34, v35
	v_permlane16_swap_b32_e32 v190, v192
	v_permlane16_swap_b32_e32 v191, v193
	v_permlane16_swap_b32_e32 v194, v196
	v_permlane16_swap_b32_e32 v195, v197
	s_add_u32 s66, s62, 0x48000
	s_addc_u32 s67, s63, 0
	global_store_dwordx4 v152, v[190:193], s[66:67]
	global_store_dwordx4 v152, v[194:197], s[66:67] offset:256
	s_waitcnt vmcnt(10)
	v_swap_b32_e32 v233, v234
	v_swap_b32_e32 v237, v238
	v_swap_b32_e32 v241, v242
	v_swap_b32_e32 v245, v246
	v_pk_mul_f32 v[186:187], v[24:25], v[234:235]
	v_pk_mul_f32 v[188:189], v[28:29], v[234:235]
	v_pk_fma_f32 v[28:29], v[28:29], v[232:233], v[186:187] neg_lo:[0,0,1] neg_hi:[0,0,1]
	v_pk_fma_f32 v[24:25], v[24:25], v[232:233], v[188:189]
	v_pk_mul_f32 v[28:29], v[28:29], v[154:155]
	v_pk_mul_f32 v[24:25], v[24:25], v[154:155]
	v_pk_mul_f32 v[186:187], v[26:27], v[238:239]
	v_pk_mul_f32 v[188:189], v[30:31], v[238:239]
	v_pk_fma_f32 v[30:31], v[30:31], v[236:237], v[186:187] neg_lo:[0,0,1] neg_hi:[0,0,1]
	v_pk_fma_f32 v[26:27], v[26:27], v[236:237], v[188:189]
	v_pk_mul_f32 v[30:31], v[30:31], v[154:155]
	v_pk_mul_f32 v[26:27], v[26:27], v[154:155]
	v_pk_mul_f32 v[186:187], v[16:17], v[242:243]
	v_pk_mul_f32 v[188:189], v[20:21], v[242:243]
	v_pk_fma_f32 v[20:21], v[20:21], v[240:241], v[186:187] neg_lo:[0,0,1] neg_hi:[0,0,1]
	v_pk_fma_f32 v[16:17], v[16:17], v[240:241], v[188:189]
	v_pk_mul_f32 v[20:21], v[20:21], v[154:155]
	v_pk_mul_f32 v[16:17], v[16:17], v[154:155]
	v_pk_mul_f32 v[186:187], v[18:19], v[246:247]
	v_pk_mul_f32 v[188:189], v[22:23], v[246:247]
	v_pk_fma_f32 v[22:23], v[22:23], v[244:245], v[186:187] neg_lo:[0,0,1] neg_hi:[0,0,1]
	v_pk_fma_f32 v[18:19], v[18:19], v[244:245], v[188:189]
	v_pk_mul_f32 v[22:23], v[22:23], v[154:155]
	v_pk_mul_f32 v[18:19], v[18:19], v[154:155]
	v_cvt_pk_bf16_f32 v190, v28, v29
	v_cvt_pk_bf16_f32 v191, v30, v31
	v_cvt_pk_bf16_f32 v192, v20, v21
	v_cvt_pk_bf16_f32 v193, v22, v23
	v_cvt_pk_bf16_f32 v194, v24, v25
	v_cvt_pk_bf16_f32 v195, v26, v27
	v_cvt_pk_bf16_f32 v196, v16, v17
	v_cvt_pk_bf16_f32 v197, v18, v19
	v_permlane16_swap_b32_e32 v190, v192
	v_permlane16_swap_b32_e32 v191, v193
	v_permlane16_swap_b32_e32 v194, v196
	v_permlane16_swap_b32_e32 v195, v197
	s_add_u32 s66, s62, 0x50000
	s_addc_u32 s67, s63, 0
	global_store_dwordx4 v152, v[190:193], s[66:67]
	global_store_dwordx4 v152, v[194:197], s[66:67] offset:256
	s_waitcnt vmcnt(6)
	v_swap_b32_e32 v171, v172
	v_swap_b32_e32 v175, v176
	v_swap_b32_e32 v179, v180
	v_swap_b32_e32 v183, v184
	v_pk_mul_f32 v[186:187], v[8:9], v[172:173]
	v_pk_mul_f32 v[188:189], v[12:13], v[172:173]
	v_pk_fma_f32 v[12:13], v[12:13], v[170:171], v[186:187] neg_lo:[0,0,1] neg_hi:[0,0,1]
	v_pk_fma_f32 v[8:9], v[8:9], v[170:171], v[188:189]
	v_pk_mul_f32 v[12:13], v[12:13], v[154:155]
	v_pk_mul_f32 v[8:9], v[8:9], v[154:155]
	v_pk_mul_f32 v[186:187], v[10:11], v[176:177]
	v_pk_mul_f32 v[188:189], v[14:15], v[176:177]
	v_pk_fma_f32 v[14:15], v[14:15], v[174:175], v[186:187] neg_lo:[0,0,1] neg_hi:[0,0,1]
	v_pk_fma_f32 v[10:11], v[10:11], v[174:175], v[188:189]
	v_pk_mul_f32 v[14:15], v[14:15], v[154:155]
	v_pk_mul_f32 v[10:11], v[10:11], v[154:155]
	v_pk_mul_f32 v[186:187], v[0:1], v[180:181]
	v_pk_mul_f32 v[188:189], v[4:5], v[180:181]
	v_pk_fma_f32 v[4:5], v[4:5], v[178:179], v[186:187] neg_lo:[0,0,1] neg_hi:[0,0,1]
	v_pk_fma_f32 v[0:1], v[0:1], v[178:179], v[188:189]
	v_pk_mul_f32 v[4:5], v[4:5], v[154:155]
	v_pk_mul_f32 v[0:1], v[0:1], v[154:155]
	v_pk_mul_f32 v[186:187], v[2:3], v[184:185]
	v_pk_mul_f32 v[188:189], v[6:7], v[184:185]
	v_pk_fma_f32 v[6:7], v[6:7], v[182:183], v[186:187] neg_lo:[0,0,1] neg_hi:[0,0,1]
	v_pk_fma_f32 v[2:3], v[2:3], v[182:183], v[188:189]
	v_pk_mul_f32 v[6:7], v[6:7], v[154:155]
	v_pk_mul_f32 v[2:3], v[2:3], v[154:155]
	v_cvt_pk_bf16_f32 v190, v12, v13
	v_cvt_pk_bf16_f32 v191, v14, v15
	v_cvt_pk_bf16_f32 v192, v4, v5
	v_cvt_pk_bf16_f32 v193, v6, v7
	v_cvt_pk_bf16_f32 v194, v8, v9
	v_cvt_pk_bf16_f32 v195, v10, v11
	v_cvt_pk_bf16_f32 v196, v0, v1
	v_cvt_pk_bf16_f32 v197, v2, v3
	v_permlane16_swap_b32_e32 v190, v192
	v_permlane16_swap_b32_e32 v191, v193
	v_permlane16_swap_b32_e32 v194, v196
	v_permlane16_swap_b32_e32 v195, v197
	s_add_u32 s66, s62, 0x58000
	s_addc_u32 s67, s63, 0
	global_store_dwordx4 v152, v[190:193], s[66:67]
	global_store_dwordx4 v152, v[194:197], s[66:67] offset:256
	s_branch .LBB0_1002

.LBB0_1614:
	ds_read_b128 v[140:143], v149
	ds_read_b128 v[152:155], v149 offset:1024
	ds_read_b128 v[156:159], v149 offset:2048
	ds_read_b128 v[160:163], v149 offset:3072
	s_add_u32 s28, s26, 0xfffc0080
	s_addc_u32 s29, s27, -1
	s_cmp_eq_u32 s48, 12
	s_cselect_b32 s31, s17, s29
	s_cselect_b32 s30, s19, s28
	s_cselect_b32 s29, s44, s47
	s_cselect_b32 s28, s45, s46
	v_lshl_add_u64 v[144:145], s[26:27], 0, v[132:133]
	s_add_i32 m0, s25, 0xc000
	ds_read_b128 v[164:167], v150
	ds_read_b128 v[168:171], v150 offset:1024
	ds_read_b128 v[172:175], v150 offset:2048
	ds_read_b128 v[176:179], v150 offset:3072
	ds_read_b128 v[180:183], v150 offset:4096
	ds_read_b128 v[184:187], v150 offset:5120
	ds_read_b128 v[188:191], v150 offset:6144
	ds_read_b128 v[192:195], v150 offset:7168
	global_load_lds_dwordx4 v[144:145], off
	v_lshl_add_u64 v[144:145], s[26:27], 0, v[134:135]
	s_add_i32 m0, s25, 0xe000
	s_nop 0
	global_load_lds_dwordx4 v[144:145], off
	s_waitcnt lgkmcnt(8)
	s_barrier
	s_waitcnt lgkmcnt(0)
	s_setprio 1
	s_waitcnt lgkmcnt(0)
	v_mfma_f32_16x16x32_bf16 v[124:127], v[140:143], v[164:167], v[124:127]
	v_mfma_f32_16x16x32_bf16 v[120:123], v[156:159], v[164:167], v[120:123]
	v_mfma_f32_16x16x32_bf16 v[108:111], v[140:143], v[172:175], v[108:111]
	v_mfma_f32_16x16x32_bf16 v[104:107], v[156:159], v[172:175], v[104:107]
	v_mfma_f32_16x16x32_bf16 v[92:95], v[140:143], v[180:183], v[92:95]
	v_mfma_f32_16x16x32_bf16 v[88:91], v[156:159], v[180:183], v[88:91]
	v_mfma_f32_16x16x32_bf16 v[76:79], v[140:143], v[188:191], v[76:79]
	v_mfma_f32_16x16x32_bf16 v[72:75], v[156:159], v[188:191], v[72:75]
	v_mfma_f32_16x16x32_bf16 v[124:127], v[152:155], v[168:171], v[124:127]
	v_mfma_f32_16x16x32_bf16 v[120:123], v[160:163], v[168:171], v[120:123]
	v_mfma_f32_16x16x32_bf16 v[108:111], v[152:155], v[176:179], v[108:111]
	v_mfma_f32_16x16x32_bf16 v[104:107], v[160:163], v[176:179], v[104:107]
	v_mfma_f32_16x16x32_bf16 v[92:95], v[152:155], v[184:187], v[92:95]
	v_mfma_f32_16x16x32_bf16 v[88:91], v[160:163], v[184:187], v[88:91]
	v_mfma_f32_16x16x32_bf16 v[76:79], v[152:155], v[192:195], v[76:79]
	v_mfma_f32_16x16x32_bf16 v[72:75], v[160:163], v[192:195], v[72:75]
	s_setprio 0
	s_barrier
	s_add_i32 s49, s42, s35
	v_lshl_add_u64 v[144:145], s[28:29], 0, v[130:131]
	s_mov_b32 m0, s49
	ds_read_b128 v[200:203], v151
	ds_read_b128 v[204:207], v151 offset:1024
	ds_read_b128 v[208:211], v151 offset:2048
	ds_read_b128 v[212:215], v151 offset:3072
	global_load_lds_dwordx4 v[144:145], off
	v_lshl_add_u64 v[196:197], s[28:29], 0, v[128:129]
	s_add_i32 m0, s49, 0x2000
	s_nop 0
	global_load_lds_dwordx4 v[196:197], off
	s_barrier
	s_waitcnt lgkmcnt(0)
	s_setprio 1
	s_waitcnt lgkmcnt(0)
	v_mfma_f32_16x16x32_bf16 v[116:119], v[200:203], v[164:167], v[116:119]
	v_mfma_f32_16x16x32_bf16 v[112:115], v[208:211], v[164:167], v[112:115]
	v_mfma_f32_16x16x32_bf16 v[100:103], v[200:203], v[172:175], v[100:103]
	v_mfma_f32_16x16x32_bf16 v[96:99], v[208:211], v[172:175], v[96:99]
	v_mfma_f32_16x16x32_bf16 v[84:87], v[200:203], v[180:183], v[84:87]
	v_mfma_f32_16x16x32_bf16 v[80:83], v[208:211], v[180:183], v[80:83]
	v_mfma_f32_16x16x32_bf16 v[68:71], v[200:203], v[188:191], v[68:71]
	v_mfma_f32_16x16x32_bf16 v[64:67], v[208:211], v[188:191], v[64:67]
	v_mfma_f32_16x16x32_bf16 v[116:119], v[204:207], v[168:171], v[116:119]
	v_mfma_f32_16x16x32_bf16 v[112:115], v[212:215], v[168:171], v[112:115]
	v_mfma_f32_16x16x32_bf16 v[100:103], v[204:207], v[176:179], v[100:103]
	v_mfma_f32_16x16x32_bf16 v[96:99], v[212:215], v[176:179], v[96:99]
	v_mfma_f32_16x16x32_bf16 v[84:87], v[204:207], v[184:187], v[84:87]
	v_mfma_f32_16x16x32_bf16 v[80:83], v[212:215], v[184:187], v[80:83]
	v_mfma_f32_16x16x32_bf16 v[68:71], v[204:207], v[192:195], v[68:71]
	v_mfma_f32_16x16x32_bf16 v[64:67], v[212:215], v[192:195], v[64:67]
	s_setprio 0
	s_mov_b32 m0, s25
	v_lshl_add_u64 v[216:217], s[30:31], 0, v[130:131]
	s_barrier
	ds_read_b128 v[164:167], v150 offset:16384
	ds_read_b128 v[168:171], v150 offset:17408
	ds_read_b128 v[172:175], v150 offset:18432
	ds_read_b128 v[176:179], v150 offset:19456
	ds_read_b128 v[180:183], v150 offset:20480
	ds_read_b128 v[184:187], v150 offset:21504
	ds_read_b128 v[188:191], v150 offset:22528
	ds_read_b128 v[192:195], v150 offset:23552
	global_load_lds_dwordx4 v[216:217], off
	v_lshl_add_u64 v[218:219], s[30:31], 0, v[128:129]
	s_mov_b32 m0, s36
	s_nop 0
	global_load_lds_dwordx4 v[218:219], off
	s_barrier
	s_waitcnt lgkmcnt(0)
	s_setprio 1
	s_waitcnt lgkmcnt(0)
	v_mfma_f32_16x16x32_bf16 v[60:63], v[140:143], v[164:167], v[60:63]
	v_mfma_f32_16x16x32_bf16 v[56:59], v[156:159], v[164:167], v[56:59]
	v_mfma_f32_16x16x32_bf16 v[44:47], v[140:143], v[172:175], v[44:47]
	v_mfma_f32_16x16x32_bf16 v[40:43], v[156:159], v[172:175], v[40:43]
	v_mfma_f32_16x16x32_bf16 v[28:31], v[140:143], v[180:183], v[28:31]
	v_mfma_f32_16x16x32_bf16 v[24:27], v[156:159], v[180:183], v[24:27]
	v_mfma_f32_16x16x32_bf16 v[12:15], v[140:143], v[188:191], v[12:15]
	v_mfma_f32_16x16x32_bf16 v[8:11], v[156:159], v[188:191], v[8:11]
	v_mfma_f32_16x16x32_bf16 v[60:63], v[152:155], v[168:171], v[60:63]
	v_mfma_f32_16x16x32_bf16 v[56:59], v[160:163], v[168:171], v[56:59]
	v_mfma_f32_16x16x32_bf16 v[44:47], v[152:155], v[176:179], v[44:47]
	v_mfma_f32_16x16x32_bf16 v[40:43], v[160:163], v[176:179], v[40:43]
	v_mfma_f32_16x16x32_bf16 v[28:31], v[152:155], v[184:187], v[28:31]
	v_mfma_f32_16x16x32_bf16 v[24:27], v[160:163], v[184:187], v[24:27]
	v_mfma_f32_16x16x32_bf16 v[12:15], v[152:155], v[192:195], v[12:15]
	v_mfma_f32_16x16x32_bf16 v[8:11], v[160:163], v[192:195], v[8:11]
	s_setprio 0
	s_barrier
	s_add_u32 s50, s28, 0x40000
	s_addc_u32 s51, s29, 0
	s_add_i32 s49, s43, s35
	v_lshl_add_u64 v[140:141], s[50:51], 0, v[130:131]
	s_mov_b32 m0, s49
	s_nop 0
	global_load_lds_dwordx4 v[140:141], off
	v_lshl_add_u64 v[140:141], s[50:51], 0, v[128:129]
	s_add_i32 m0, s49, 0x2000
	s_nop 0
	global_load_lds_dwordx4 v[140:141], off
	s_waitcnt vmcnt(6)
	s_barrier
	s_setprio 1
	v_mfma_f32_16x16x32_bf16 v[52:55], v[200:203], v[164:167], v[52:55]
	v_mfma_f32_16x16x32_bf16 v[48:51], v[208:211], v[164:167], v[48:51]
	v_mfma_f32_16x16x32_bf16 v[36:39], v[200:203], v[172:175], v[36:39]
	v_mfma_f32_16x16x32_bf16 v[32:35], v[208:211], v[172:175], v[32:35]
	v_mfma_f32_16x16x32_bf16 v[20:23], v[200:203], v[180:183], v[20:23]
	v_mfma_f32_16x16x32_bf16 v[16:19], v[208:211], v[180:183], v[16:19]
	v_mfma_f32_16x16x32_bf16 v[4:7], v[200:203], v[188:191], v[4:7]
	v_mfma_f32_16x16x32_bf16 v[0:3], v[208:211], v[188:191], v[0:3]
	v_mfma_f32_16x16x32_bf16 v[52:55], v[204:207], v[168:171], v[52:55]
	v_mfma_f32_16x16x32_bf16 v[48:51], v[212:215], v[168:171], v[48:51]
	v_mfma_f32_16x16x32_bf16 v[36:39], v[204:207], v[176:179], v[36:39]
	v_mfma_f32_16x16x32_bf16 v[32:35], v[212:215], v[176:179], v[32:35]
	v_mfma_f32_16x16x32_bf16 v[20:23], v[204:207], v[184:187], v[20:23]
	v_mfma_f32_16x16x32_bf16 v[16:19], v[212:215], v[184:187], v[16:19]
	v_mfma_f32_16x16x32_bf16 v[4:7], v[204:207], v[192:195], v[4:7]
	v_mfma_f32_16x16x32_bf16 v[0:3], v[212:215], v[192:195], v[0:3]
	s_setprio 0
	s_add_i32 s49, 0, 0x18000
	v_add_u32_e32 v160, s49, v147
	s_barrier
	ds_read_b128 v[140:143], v160
	ds_read_b128 v[152:155], v160 offset:1024
	ds_read_b128 v[156:159], v160 offset:2048
	ds_read_b128 v[160:163], v160 offset:3072
	s_add_u32 s30, s30, 0x40000
	s_addc_u32 s31, s31, 0
	s_mov_b32 m0, s37
	v_lshl_add_u64 v[200:201], s[30:31], 0, v[130:131]
	ds_read_b128 v[164:167], v150 offset:32768
	ds_read_b128 v[168:171], v150 offset:33792
	ds_read_b128 v[172:175], v150 offset:34816
	ds_read_b128 v[176:179], v150 offset:35840
	ds_read_b128 v[180:183], v150 offset:36864
	ds_read_b128 v[184:187], v150 offset:37888
	ds_read_b128 v[188:191], v150 offset:38912
	ds_read_b128 v[192:195], v150 offset:39936
	global_load_lds_dwordx4 v[200:201], off
	v_lshl_add_u64 v[200:201], s[30:31], 0, v[128:129]
	s_mov_b32 m0, s38
	s_nop 0
	global_load_lds_dwordx4 v[200:201], off
	s_waitcnt lgkmcnt(8)
	s_barrier
	s_waitcnt lgkmcnt(0)
	s_setprio 1
	s_waitcnt lgkmcnt(0)
	v_mfma_f32_16x16x32_bf16 v[124:127], v[140:143], v[164:167], v[124:127]
	v_mfma_f32_16x16x32_bf16 v[120:123], v[156:159], v[164:167], v[120:123]
	v_mfma_f32_16x16x32_bf16 v[108:111], v[140:143], v[172:175], v[108:111]
	v_mfma_f32_16x16x32_bf16 v[104:107], v[156:159], v[172:175], v[104:107]
	v_mfma_f32_16x16x32_bf16 v[92:95], v[140:143], v[180:183], v[92:95]
	v_mfma_f32_16x16x32_bf16 v[88:91], v[156:159], v[180:183], v[88:91]
	v_mfma_f32_16x16x32_bf16 v[76:79], v[140:143], v[188:191], v[76:79]
	v_mfma_f32_16x16x32_bf16 v[72:75], v[156:159], v[188:191], v[72:75]
	v_mfma_f32_16x16x32_bf16 v[124:127], v[152:155], v[168:171], v[124:127]
	v_mfma_f32_16x16x32_bf16 v[120:123], v[160:163], v[168:171], v[120:123]
	v_mfma_f32_16x16x32_bf16 v[108:111], v[152:155], v[176:179], v[108:111]
	v_mfma_f32_16x16x32_bf16 v[104:107], v[160:163], v[176:179], v[104:107]
	v_mfma_f32_16x16x32_bf16 v[92:95], v[152:155], v[184:187], v[92:95]
	v_mfma_f32_16x16x32_bf16 v[88:91], v[160:163], v[184:187], v[88:91]
	v_mfma_f32_16x16x32_bf16 v[76:79], v[152:155], v[192:195], v[76:79]
	v_mfma_f32_16x16x32_bf16 v[72:75], v[160:163], v[192:195], v[72:75]
	s_setprio 0
	s_barrier
	s_add_i32 s30, 0, 0x1c000
	s_add_i32 s31, s49, s35
	v_add_u32_e32 v199, s30, v147
	v_lshl_add_u64 v[144:145], v[144:145], 0, s[6:7]
	s_mov_b32 m0, s31
	ds_read_b128 v[200:203], v199
	ds_read_b128 v[204:207], v199 offset:1024
	ds_read_b128 v[208:211], v199 offset:2048
	ds_read_b128 v[212:215], v199 offset:3072
	global_load_lds_dwordx4 v[144:145], off
	v_lshl_add_u64 v[144:145], v[196:197], 0, s[6:7]
	s_add_i32 m0, s31, 0x2000
	s_nop 0
	global_load_lds_dwordx4 v[144:145], off
	s_barrier
	s_waitcnt lgkmcnt(0)
	s_setprio 1
	s_waitcnt lgkmcnt(0)
	v_mfma_f32_16x16x32_bf16 v[116:119], v[200:203], v[164:167], v[116:119]
	v_mfma_f32_16x16x32_bf16 v[112:115], v[208:211], v[164:167], v[112:115]
	v_mfma_f32_16x16x32_bf16 v[100:103], v[200:203], v[172:175], v[100:103]
	v_mfma_f32_16x16x32_bf16 v[96:99], v[208:211], v[172:175], v[96:99]
	v_mfma_f32_16x16x32_bf16 v[84:87], v[200:203], v[180:183], v[84:87]
	v_mfma_f32_16x16x32_bf16 v[80:83], v[208:211], v[180:183], v[80:83]
	v_mfma_f32_16x16x32_bf16 v[68:71], v[200:203], v[188:191], v[68:71]
	v_mfma_f32_16x16x32_bf16 v[64:67], v[208:211], v[188:191], v[64:67]
	v_mfma_f32_16x16x32_bf16 v[116:119], v[204:207], v[168:171], v[116:119]
	v_mfma_f32_16x16x32_bf16 v[112:115], v[212:215], v[168:171], v[112:115]
	v_mfma_f32_16x16x32_bf16 v[100:103], v[204:207], v[176:179], v[100:103]
	v_mfma_f32_16x16x32_bf16 v[96:99], v[212:215], v[176:179], v[96:99]
	v_mfma_f32_16x16x32_bf16 v[84:87], v[204:207], v[184:187], v[84:87]
	v_mfma_f32_16x16x32_bf16 v[80:83], v[212:215], v[184:187], v[80:83]
	v_mfma_f32_16x16x32_bf16 v[68:71], v[204:207], v[192:195], v[68:71]
	v_mfma_f32_16x16x32_bf16 v[64:67], v[212:215], v[192:195], v[64:67]
	s_setprio 0
	s_mov_b32 m0, s40
	v_lshl_add_u64 v[144:145], v[216:217], 0, s[6:7]
	s_barrier
	ds_read_b128 v[164:167], v150 offset:49152
	ds_read_b128 v[168:171], v150 offset:50176
	ds_read_b128 v[172:175], v150 offset:51200
	ds_read_b128 v[176:179], v150 offset:52224
	ds_read_b128 v[180:183], v150 offset:53248
	ds_read_b128 v[184:187], v150 offset:54272
	ds_read_b128 v[188:191], v150 offset:55296
	ds_read_b128 v[192:195], v150 offset:56320
	global_load_lds_dwordx4 v[144:145], off
	v_lshl_add_u64 v[144:145], v[218:219], 0, s[6:7]
	s_mov_b32 m0, s41
	s_nop 0
	global_load_lds_dwordx4 v[144:145], off
	s_barrier
	s_waitcnt lgkmcnt(0)
	s_setprio 1
	s_waitcnt lgkmcnt(0)
	v_mfma_f32_16x16x32_bf16 v[60:63], v[140:143], v[164:167], v[60:63]
	v_mfma_f32_16x16x32_bf16 v[56:59], v[156:159], v[164:167], v[56:59]
	v_mfma_f32_16x16x32_bf16 v[44:47], v[140:143], v[172:175], v[44:47]
	v_mfma_f32_16x16x32_bf16 v[40:43], v[156:159], v[172:175], v[40:43]
	v_mfma_f32_16x16x32_bf16 v[28:31], v[140:143], v[180:183], v[28:31]
	v_mfma_f32_16x16x32_bf16 v[24:27], v[156:159], v[180:183], v[24:27]
	v_mfma_f32_16x16x32_bf16 v[12:15], v[140:143], v[188:191], v[12:15]
	v_mfma_f32_16x16x32_bf16 v[8:11], v[156:159], v[188:191], v[8:11]
	v_mfma_f32_16x16x32_bf16 v[60:63], v[152:155], v[168:171], v[60:63]
	v_mfma_f32_16x16x32_bf16 v[56:59], v[160:163], v[168:171], v[56:59]
	v_mfma_f32_16x16x32_bf16 v[44:47], v[152:155], v[176:179], v[44:47]
	v_mfma_f32_16x16x32_bf16 v[40:43], v[160:163], v[176:179], v[40:43]
	v_mfma_f32_16x16x32_bf16 v[28:31], v[152:155], v[184:187], v[28:31]
	v_mfma_f32_16x16x32_bf16 v[24:27], v[160:163], v[184:187], v[24:27]
	v_mfma_f32_16x16x32_bf16 v[12:15], v[152:155], v[192:195], v[12:15]
	v_mfma_f32_16x16x32_bf16 v[8:11], v[160:163], v[192:195], v[8:11]
	s_setprio 0
	s_barrier
	s_add_u32 s28, s28, 0x40080
	s_addc_u32 s29, s29, 0
	s_add_i32 s30, s30, s35
	v_lshl_add_u64 v[140:141], s[28:29], 0, v[130:131]
	s_mov_b32 m0, s30
	s_nop 0
	global_load_lds_dwordx4 v[140:141], off
	v_lshl_add_u64 v[140:141], s[28:29], 0, v[128:129]
	s_add_i32 m0, s30, 0x2000
	s_nop 0
	global_load_lds_dwordx4 v[140:141], off
	s_waitcnt vmcnt(6)
	s_barrier
	s_setprio 1
	v_mfma_f32_16x16x32_bf16 v[52:55], v[200:203], v[164:167], v[52:55]
	v_mfma_f32_16x16x32_bf16 v[48:51], v[208:211], v[164:167], v[48:51]
	v_mfma_f32_16x16x32_bf16 v[36:39], v[200:203], v[172:175], v[36:39]
	v_mfma_f32_16x16x32_bf16 v[32:35], v[208:211], v[172:175], v[32:35]
	v_mfma_f32_16x16x32_bf16 v[20:23], v[200:203], v[180:183], v[20:23]
	v_mfma_f32_16x16x32_bf16 v[16:19], v[208:211], v[180:183], v[16:19]
	v_mfma_f32_16x16x32_bf16 v[4:7], v[200:203], v[188:191], v[4:7]
	v_mfma_f32_16x16x32_bf16 v[0:3], v[208:211], v[188:191], v[0:3]
	v_mfma_f32_16x16x32_bf16 v[52:55], v[204:207], v[168:171], v[52:55]
	v_mfma_f32_16x16x32_bf16 v[48:51], v[212:215], v[168:171], v[48:51]
	v_mfma_f32_16x16x32_bf16 v[36:39], v[204:207], v[176:179], v[36:39]
	v_mfma_f32_16x16x32_bf16 v[32:35], v[212:215], v[176:179], v[32:35]
	v_mfma_f32_16x16x32_bf16 v[20:23], v[204:207], v[184:187], v[20:23]
	v_mfma_f32_16x16x32_bf16 v[16:19], v[212:215], v[184:187], v[16:19]
	v_mfma_f32_16x16x32_bf16 v[4:7], v[204:207], v[192:195], v[4:7]
	v_mfma_f32_16x16x32_bf16 v[0:3], v[212:215], v[192:195], v[0:3]
	s_setprio 0
	s_add_i32 s48, s48, 2
	s_add_u32 s26, s26, 0x100
	s_addc_u32 s27, s27, 0
	s_add_u32 s46, s46, 0x100
	s_addc_u32 s47, s47, 0
	s_cmp_gt_u32 s48, 13
	s_barrier
	s_cbranch_scc0 .LBB0_1614
	v_lshl_add_u32 v190, s24, 8, v146
	v_lshl_or_b32 v191, s33, 8, v148
	v_lshl_add_u32 v184, v190, 10, v191
	v_and_b32_e32 v190, 16, v198
	v_lshrrev_b32_e32 v191, 1, v190
	v_add_u32_e32 v190, v190, v191
	v_lshl_add_u32 v176, v184, 1, v190
	v_add_u32_e32 v177, 0x8000, v176
	v_add_u32_e32 v178, 0x10000, v176
	v_add_u32_e32 v179, 0x18000, v176
	v_add_u32_e32 v180, 0x40000, v176
	v_add_u32_e32 v181, 0x48000, v176
	v_add_u32_e32 v182, 0x50000, v176
	v_add_u32_e32 v183, 0x58000, v176
	v_and_b32_e32 v190, 8, v198
	v_sub_u32_e32 v191, v146, v190
	v_lshl_add_u32 v191, s24, 8, v191
	v_lshlrev_b32_e32 v184, 12, v191
	v_lshl_add_u32 v184, v190, 3, v184
	v_bfe_u32 v190, v198, 4, 2
	v_lshl_add_u32 v184, v190, 4, v184
	v_bfe_u32 v190, v198, 6, 2
	v_lshl_add_u32 v184, v190, 7, v184
	s_lshl_b32 s60, s33, 10
	v_add_u32_e32 v184, s60, v184
	v_mov_b32_e32 v186, 0xbfb8aa3b
	v_mov_b32_e32 v187, 0xbfb8aa3b
	v_mov_b32_e32 v188, 1.0
	v_mov_b32_e32 v189, 1.0
	s_and_b64 vcc, exec, s[0:1]
	global_load_dwordx4 v[200:203], v176, s[88:89]
	global_load_dwordx4 v[204:207], v176, s[4:5]
	global_load_dwordx4 v[208:211], v176, s[88:89] offset:256
	global_load_dwordx4 v[212:215], v176, s[4:5] offset:256
	global_load_dwordx4 v[216:219], v177, s[88:89]
	global_load_dwordx4 v[220:223], v177, s[4:5]
	global_load_dwordx4 v[224:227], v177, s[88:89] offset:256
	global_load_dwordx4 v[228:231], v177, s[4:5] offset:256
	global_load_dwordx4 v[232:235], v178, s[88:89]
	global_load_dwordx4 v[236:239], v178, s[4:5]
	global_load_dwordx4 v[240:243], v178, s[88:89] offset:256
	global_load_dwordx4 v[244:247], v178, s[4:5] offset:256
	global_load_dwordx4 v[152:155], v179, s[88:89]
	global_load_dwordx4 v[156:159], v179, s[4:5]
	global_load_dwordx4 v[160:163], v179, s[88:89] offset:256
	global_load_dwordx4 v[164:167], v179, s[4:5] offset:256
	v_pk_mul_f32 v[124:125], v[124:125], v[186:187]
	v_pk_mul_f32 v[126:127], v[126:127], v[186:187]
	v_pk_mul_f32 v[120:121], v[120:121], v[186:187]
	v_pk_mul_f32 v[122:123], v[122:123], v[186:187]
	v_exp_f32_e32 v124, v124
	v_exp_f32_e32 v125, v125
	v_exp_f32_e32 v126, v126
	v_exp_f32_e32 v127, v127
	v_exp_f32_e32 v120, v120
	v_exp_f32_e32 v121, v121
	v_exp_f32_e32 v122, v122
	v_exp_f32_e32 v123, v123
	v_pk_add_f32 v[124:125], v[124:125], v[188:189]
	v_pk_add_f32 v[126:127], v[126:127], v[188:189]
	v_pk_add_f32 v[120:121], v[120:121], v[188:189]
	v_pk_add_f32 v[122:123], v[122:123], v[188:189]
	v_rcp_f32_e32 v124, v124
	v_rcp_f32_e32 v125, v125
	v_rcp_f32_e32 v126, v126
	v_rcp_f32_e32 v127, v127
	v_rcp_f32_e32 v120, v120
	v_rcp_f32_e32 v121, v121
	v_rcp_f32_e32 v122, v122
	v_rcp_f32_e32 v123, v123
	s_waitcnt vmcnt(14)
	v_permlane16_swap_b32_e32 v200, v202
	v_permlane16_swap_b32_e32 v201, v203
	v_permlane16_swap_b32_e32 v204, v206
	v_permlane16_swap_b32_e32 v205, v207
	v_lshlrev_b32_e32 v168, 16, v200
	v_and_b32_e32 v169, 0xffff0000, v200
	v_lshlrev_b32_e32 v200, 16, v201
	v_and_b32_e32 v201, 0xffff0000, v201
	v_lshlrev_b32_e32 v170, 16, v202
	v_and_b32_e32 v171, 0xffff0000, v202
	v_lshlrev_b32_e32 v202, 16, v203
	v_and_b32_e32 v203, 0xffff0000, v203
	v_lshlrev_b32_e32 v172, 16, v204
	v_and_b32_e32 v173, 0xffff0000, v204
	v_lshlrev_b32_e32 v204, 16, v205
	v_and_b32_e32 v205, 0xffff0000, v205
	v_lshlrev_b32_e32 v174, 16, v206
	v_and_b32_e32 v175, 0xffff0000, v206
	v_lshlrev_b32_e32 v206, 16, v207
	v_and_b32_e32 v207, 0xffff0000, v207
	v_pk_fma_f32 v[124:125], v[124:125], v[172:173], v[168:169]
	v_pk_fma_f32 v[126:127], v[126:127], v[204:205], v[200:201]
	v_pk_fma_f32 v[120:121], v[120:121], v[174:175], v[170:171]
	v_pk_fma_f32 v[122:123], v[122:123], v[206:207], v[202:203]
	v_mov_b32_e32 v185, v184
	v_add_u32_e32 v192, 0x8000, v184
	v_mov_b32_e32 v172, v120
	v_mov_b32_e32 v173, v121
	v_mov_b32_e32 v174, v122
	v_mov_b32_e32 v175, v123
	v_mov_b32_dpp v120, v124 row_ror:8 row_mask:0xf bank_mask:0x3
	v_mov_b32_dpp v121, v125 row_ror:8 row_mask:0xf bank_mask:0x3
	v_mov_b32_dpp v122, v126 row_ror:8 row_mask:0xf bank_mask:0x3
	v_mov_b32_dpp v123, v127 row_ror:8 row_mask:0xf bank_mask:0x3
	v_mov_b32_dpp v124, v172 row_ror:8 row_mask:0xf bank_mask:0xc
	v_mov_b32_dpp v125, v173 row_ror:8 row_mask:0xf bank_mask:0xc
	v_mov_b32_dpp v126, v174 row_ror:8 row_mask:0xf bank_mask:0xc
	v_mov_b32_dpp v127, v175 row_ror:8 row_mask:0xf bank_mask:0xc
	global_store_dwordx4 v185, v[124:127], s[92:93]
	global_store_dwordx4 v192, v[120:123], s[92:93]
	global_load_dwordx4 v[200:203], v180, s[88:89]
	global_load_dwordx4 v[204:207], v180, s[4:5]
	v_pk_mul_f32 v[116:117], v[116:117], v[186:187]
	v_pk_mul_f32 v[118:119], v[118:119], v[186:187]
	v_pk_mul_f32 v[112:113], v[112:113], v[186:187]
	v_pk_mul_f32 v[114:115], v[114:115], v[186:187]
	v_exp_f32_e32 v116, v116
	v_exp_f32_e32 v117, v117
	v_exp_f32_e32 v118, v118
	v_exp_f32_e32 v119, v119
	v_exp_f32_e32 v112, v112
	v_exp_f32_e32 v113, v113
	v_exp_f32_e32 v114, v114
	v_exp_f32_e32 v115, v115
	v_pk_add_f32 v[116:117], v[116:117], v[188:189]
	v_pk_add_f32 v[118:119], v[118:119], v[188:189]
	v_pk_add_f32 v[112:113], v[112:113], v[188:189]
	v_pk_add_f32 v[114:115], v[114:115], v[188:189]
	v_rcp_f32_e32 v116, v116
	v_rcp_f32_e32 v117, v117
	v_rcp_f32_e32 v118, v118
	v_rcp_f32_e32 v119, v119
	v_rcp_f32_e32 v112, v112
	v_rcp_f32_e32 v113, v113
	v_rcp_f32_e32 v114, v114
	v_rcp_f32_e32 v115, v115
	s_waitcnt vmcnt(16)
	v_permlane16_swap_b32_e32 v208, v210
	v_permlane16_swap_b32_e32 v209, v211
	v_permlane16_swap_b32_e32 v212, v214
	v_permlane16_swap_b32_e32 v213, v215
	v_lshlrev_b32_e32 v168, 16, v208
	v_and_b32_e32 v169, 0xffff0000, v208
	v_lshlrev_b32_e32 v208, 16, v209
	v_and_b32_e32 v209, 0xffff0000, v209
	v_lshlrev_b32_e32 v170, 16, v210
	v_and_b32_e32 v171, 0xffff0000, v210
	v_lshlrev_b32_e32 v210, 16, v211
	v_and_b32_e32 v211, 0xffff0000, v211
	v_lshlrev_b32_e32 v172, 16, v212
	v_and_b32_e32 v173, 0xffff0000, v212
	v_lshlrev_b32_e32 v212, 16, v213
	v_and_b32_e32 v213, 0xffff0000, v213
	v_lshlrev_b32_e32 v174, 16, v214
	v_and_b32_e32 v175, 0xffff0000, v214
	v_lshlrev_b32_e32 v214, 16, v215
	v_and_b32_e32 v215, 0xffff0000, v215
	v_pk_fma_f32 v[116:117], v[116:117], v[172:173], v[168:169]
	v_pk_fma_f32 v[118:119], v[118:119], v[212:213], v[208:209]
	v_pk_fma_f32 v[112:113], v[112:113], v[174:175], v[170:171]
	v_pk_fma_f32 v[114:115], v[114:115], v[214:215], v[210:211]
	v_mov_b32_e32 v172, v112
	v_mov_b32_e32 v173, v113
	v_mov_b32_e32 v174, v114
	v_mov_b32_e32 v175, v115
	v_mov_b32_dpp v112, v116 row_ror:8 row_mask:0xf bank_mask:0x3
	v_mov_b32_dpp v113, v117 row_ror:8 row_mask:0xf bank_mask:0x3
	v_mov_b32_dpp v114, v118 row_ror:8 row_mask:0xf bank_mask:0x3
	v_mov_b32_dpp v115, v119 row_ror:8 row_mask:0xf bank_mask:0x3
	v_mov_b32_dpp v116, v172 row_ror:8 row_mask:0xf bank_mask:0xc
	v_mov_b32_dpp v117, v173 row_ror:8 row_mask:0xf bank_mask:0xc
	v_mov_b32_dpp v118, v174 row_ror:8 row_mask:0xf bank_mask:0xc
	v_mov_b32_dpp v119, v175 row_ror:8 row_mask:0xf bank_mask:0xc
	global_store_dwordx4 v185, v[116:119], s[92:93] offset:512
	global_store_dwordx4 v192, v[112:115], s[92:93] offset:512
	global_load_dwordx4 v[208:211], v180, s[88:89] offset:256
	global_load_dwordx4 v[212:215], v180, s[4:5] offset:256
	v_pk_mul_f32 v[108:109], v[108:109], v[186:187]
	v_pk_mul_f32 v[110:111], v[110:111], v[186:187]
	v_pk_mul_f32 v[104:105], v[104:105], v[186:187]
	v_pk_mul_f32 v[106:107], v[106:107], v[186:187]
	v_exp_f32_e32 v108, v108
	v_exp_f32_e32 v109, v109
	v_exp_f32_e32 v110, v110
	v_exp_f32_e32 v111, v111
	v_exp_f32_e32 v104, v104
	v_exp_f32_e32 v105, v105
	v_exp_f32_e32 v106, v106
	v_exp_f32_e32 v107, v107
	v_pk_add_f32 v[108:109], v[108:109], v[188:189]
	v_pk_add_f32 v[110:111], v[110:111], v[188:189]
	v_pk_add_f32 v[104:105], v[104:105], v[188:189]
	v_pk_add_f32 v[106:107], v[106:107], v[188:189]
	v_rcp_f32_e32 v108, v108
	v_rcp_f32_e32 v109, v109
	v_rcp_f32_e32 v110, v110
	v_rcp_f32_e32 v111, v111
	v_rcp_f32_e32 v104, v104
	v_rcp_f32_e32 v105, v105
	v_rcp_f32_e32 v106, v106
	v_rcp_f32_e32 v107, v107
	s_waitcnt vmcnt(18)
	v_permlane16_swap_b32_e32 v216, v218
	v_permlane16_swap_b32_e32 v217, v219
	v_permlane16_swap_b32_e32 v220, v222
	v_permlane16_swap_b32_e32 v221, v223
	v_lshlrev_b32_e32 v168, 16, v216
	v_and_b32_e32 v169, 0xffff0000, v216
	v_lshlrev_b32_e32 v216, 16, v217
	v_and_b32_e32 v217, 0xffff0000, v217
	v_lshlrev_b32_e32 v170, 16, v218
	v_and_b32_e32 v171, 0xffff0000, v218
	v_lshlrev_b32_e32 v218, 16, v219
	v_and_b32_e32 v219, 0xffff0000, v219
	v_lshlrev_b32_e32 v172, 16, v220
	v_and_b32_e32 v173, 0xffff0000, v220
	v_lshlrev_b32_e32 v220, 16, v221
	v_and_b32_e32 v221, 0xffff0000, v221
	v_lshlrev_b32_e32 v174, 16, v222
	v_and_b32_e32 v175, 0xffff0000, v222
	v_lshlrev_b32_e32 v222, 16, v223
	v_and_b32_e32 v223, 0xffff0000, v223
	v_pk_fma_f32 v[108:109], v[108:109], v[172:173], v[168:169]
	v_pk_fma_f32 v[110:111], v[110:111], v[220:221], v[216:217]
	v_pk_fma_f32 v[104:105], v[104:105], v[174:175], v[170:171]
	v_pk_fma_f32 v[106:107], v[106:107], v[222:223], v[218:219]
	v_add_u32_e32 v185, 0x10000, v184
	v_add_u32_e32 v192, 0x18000, v184
	v_mov_b32_e32 v172, v104
	v_mov_b32_e32 v173, v105
	v_mov_b32_e32 v174, v106
	v_mov_b32_e32 v175, v107
	v_mov_b32_dpp v104, v108 row_ror:8 row_mask:0xf bank_mask:0x3
	v_mov_b32_dpp v105, v109 row_ror:8 row_mask:0xf bank_mask:0x3
	v_mov_b32_dpp v106, v110 row_ror:8 row_mask:0xf bank_mask:0x3
	v_mov_b32_dpp v107, v111 row_ror:8 row_mask:0xf bank_mask:0x3
	v_mov_b32_dpp v108, v172 row_ror:8 row_mask:0xf bank_mask:0xc
	v_mov_b32_dpp v109, v173 row_ror:8 row_mask:0xf bank_mask:0xc
	v_mov_b32_dpp v110, v174 row_ror:8 row_mask:0xf bank_mask:0xc
	v_mov_b32_dpp v111, v175 row_ror:8 row_mask:0xf bank_mask:0xc
	global_store_dwordx4 v185, v[108:111], s[92:93]
	global_store_dwordx4 v192, v[104:107], s[92:93]
	global_load_dwordx4 v[216:219], v181, s[88:89]
	global_load_dwordx4 v[220:223], v181, s[4:5]
	v_pk_mul_f32 v[100:101], v[100:101], v[186:187]
	v_pk_mul_f32 v[102:103], v[102:103], v[186:187]
	v_pk_mul_f32 v[96:97], v[96:97], v[186:187]
	v_pk_mul_f32 v[98:99], v[98:99], v[186:187]
	v_exp_f32_e32 v100, v100
	v_exp_f32_e32 v101, v101
	v_exp_f32_e32 v102, v102
	v_exp_f32_e32 v103, v103
	v_exp_f32_e32 v96, v96
	v_exp_f32_e32 v97, v97
	v_exp_f32_e32 v98, v98
	v_exp_f32_e32 v99, v99
	v_pk_add_f32 v[100:101], v[100:101], v[188:189]
	v_pk_add_f32 v[102:103], v[102:103], v[188:189]
	v_pk_add_f32 v[96:97], v[96:97], v[188:189]
	v_pk_add_f32 v[98:99], v[98:99], v[188:189]
	v_rcp_f32_e32 v100, v100
	v_rcp_f32_e32 v101, v101
	v_rcp_f32_e32 v102, v102
	v_rcp_f32_e32 v103, v103
	v_rcp_f32_e32 v96, v96
	v_rcp_f32_e32 v97, v97
	v_rcp_f32_e32 v98, v98
	v_rcp_f32_e32 v99, v99
	s_waitcnt vmcnt(20)
	v_permlane16_swap_b32_e32 v224, v226
	v_permlane16_swap_b32_e32 v225, v227
	v_permlane16_swap_b32_e32 v228, v230
	v_permlane16_swap_b32_e32 v229, v231
	v_lshlrev_b32_e32 v168, 16, v224
	v_and_b32_e32 v169, 0xffff0000, v224
	v_lshlrev_b32_e32 v224, 16, v225
	v_and_b32_e32 v225, 0xffff0000, v225
	v_lshlrev_b32_e32 v170, 16, v226
	v_and_b32_e32 v171, 0xffff0000, v226
	v_lshlrev_b32_e32 v226, 16, v227
	v_and_b32_e32 v227, 0xffff0000, v227
	v_lshlrev_b32_e32 v172, 16, v228
	v_and_b32_e32 v173, 0xffff0000, v228
	v_lshlrev_b32_e32 v228, 16, v229
	v_and_b32_e32 v229, 0xffff0000, v229
	v_lshlrev_b32_e32 v174, 16, v230
	v_and_b32_e32 v175, 0xffff0000, v230
	v_lshlrev_b32_e32 v230, 16, v231
	v_and_b32_e32 v231, 0xffff0000, v231
	v_pk_fma_f32 v[100:101], v[100:101], v[172:173], v[168:169]
	v_pk_fma_f32 v[102:103], v[102:103], v[228:229], v[224:225]
	v_pk_fma_f32 v[96:97], v[96:97], v[174:175], v[170:171]
	v_pk_fma_f32 v[98:99], v[98:99], v[230:231], v[226:227]
	v_mov_b32_e32 v172, v96
	v_mov_b32_e32 v173, v97
	v_mov_b32_e32 v174, v98
	v_mov_b32_e32 v175, v99
	v_mov_b32_dpp v96, v100 row_ror:8 row_mask:0xf bank_mask:0x3
	v_mov_b32_dpp v97, v101 row_ror:8 row_mask:0xf bank_mask:0x3
	v_mov_b32_dpp v98, v102 row_ror:8 row_mask:0xf bank_mask:0x3
	v_mov_b32_dpp v99, v103 row_ror:8 row_mask:0xf bank_mask:0x3
	v_mov_b32_dpp v100, v172 row_ror:8 row_mask:0xf bank_mask:0xc
	v_mov_b32_dpp v101, v173 row_ror:8 row_mask:0xf bank_mask:0xc
	v_mov_b32_dpp v102, v174 row_ror:8 row_mask:0xf bank_mask:0xc
	v_mov_b32_dpp v103, v175 row_ror:8 row_mask:0xf bank_mask:0xc
	global_store_dwordx4 v185, v[100:103], s[92:93] offset:512
	global_store_dwordx4 v192, v[96:99], s[92:93] offset:512
	global_load_dwordx4 v[224:227], v181, s[88:89] offset:256
	global_load_dwordx4 v[228:231], v181, s[4:5] offset:256
	v_pk_mul_f32 v[92:93], v[92:93], v[186:187]
	v_pk_mul_f32 v[94:95], v[94:95], v[186:187]
	v_pk_mul_f32 v[88:89], v[88:89], v[186:187]
	v_pk_mul_f32 v[90:91], v[90:91], v[186:187]
	v_exp_f32_e32 v92, v92
	v_exp_f32_e32 v93, v93
	v_exp_f32_e32 v94, v94
	v_exp_f32_e32 v95, v95
	v_exp_f32_e32 v88, v88
	v_exp_f32_e32 v89, v89
	v_exp_f32_e32 v90, v90
	v_exp_f32_e32 v91, v91
	v_pk_add_f32 v[92:93], v[92:93], v[188:189]
	v_pk_add_f32 v[94:95], v[94:95], v[188:189]
	v_pk_add_f32 v[88:89], v[88:89], v[188:189]
	v_pk_add_f32 v[90:91], v[90:91], v[188:189]
	v_rcp_f32_e32 v92, v92
	v_rcp_f32_e32 v93, v93
	v_rcp_f32_e32 v94, v94
	v_rcp_f32_e32 v95, v95
	v_rcp_f32_e32 v88, v88
	v_rcp_f32_e32 v89, v89
	v_rcp_f32_e32 v90, v90
	v_rcp_f32_e32 v91, v91
	s_waitcnt vmcnt(22)
	v_permlane16_swap_b32_e32 v232, v234
	v_permlane16_swap_b32_e32 v233, v235
	v_permlane16_swap_b32_e32 v236, v238
	v_permlane16_swap_b32_e32 v237, v239
	v_lshlrev_b32_e32 v168, 16, v232
	v_and_b32_e32 v169, 0xffff0000, v232
	v_lshlrev_b32_e32 v232, 16, v233
	v_and_b32_e32 v233, 0xffff0000, v233
	v_lshlrev_b32_e32 v170, 16, v234
	v_and_b32_e32 v171, 0xffff0000, v234
	v_lshlrev_b32_e32 v234, 16, v235
	v_and_b32_e32 v235, 0xffff0000, v235
	v_lshlrev_b32_e32 v172, 16, v236
	v_and_b32_e32 v173, 0xffff0000, v236
	v_lshlrev_b32_e32 v236, 16, v237
	v_and_b32_e32 v237, 0xffff0000, v237
	v_lshlrev_b32_e32 v174, 16, v238
	v_and_b32_e32 v175, 0xffff0000, v238
	v_lshlrev_b32_e32 v238, 16, v239
	v_and_b32_e32 v239, 0xffff0000, v239
	v_pk_fma_f32 v[92:93], v[92:93], v[172:173], v[168:169]
	v_pk_fma_f32 v[94:95], v[94:95], v[236:237], v[232:233]
	v_pk_fma_f32 v[88:89], v[88:89], v[174:175], v[170:171]
	v_pk_fma_f32 v[90:91], v[90:91], v[238:239], v[234:235]
	v_add_u32_e32 v185, 0x20000, v184
	v_add_u32_e32 v192, 0x28000, v184
	v_mov_b32_e32 v172, v88
	v_mov_b32_e32 v173, v89
	v_mov_b32_e32 v174, v90
	v_mov_b32_e32 v175, v91
	v_mov_b32_dpp v88, v92 row_ror:8 row_mask:0xf bank_mask:0x3
	v_mov_b32_dpp v89, v93 row_ror:8 row_mask:0xf bank_mask:0x3
	v_mov_b32_dpp v90, v94 row_ror:8 row_mask:0xf bank_mask:0x3
	v_mov_b32_dpp v91, v95 row_ror:8 row_mask:0xf bank_mask:0x3
	v_mov_b32_dpp v92, v172 row_ror:8 row_mask:0xf bank_mask:0xc
	v_mov_b32_dpp v93, v173 row_ror:8 row_mask:0xf bank_mask:0xc
	v_mov_b32_dpp v94, v174 row_ror:8 row_mask:0xf bank_mask:0xc
	v_mov_b32_dpp v95, v175 row_ror:8 row_mask:0xf bank_mask:0xc
	global_store_dwordx4 v185, v[92:95], s[92:93]
	global_store_dwordx4 v192, v[88:91], s[92:93]
	global_load_dwordx4 v[232:235], v182, s[88:89]
	global_load_dwordx4 v[236:239], v182, s[4:5]
	v_pk_mul_f32 v[84:85], v[84:85], v[186:187]
	v_pk_mul_f32 v[86:87], v[86:87], v[186:187]
	v_pk_mul_f32 v[80:81], v[80:81], v[186:187]
	v_pk_mul_f32 v[82:83], v[82:83], v[186:187]
	v_exp_f32_e32 v84, v84
	v_exp_f32_e32 v85, v85
	v_exp_f32_e32 v86, v86
	v_exp_f32_e32 v87, v87
	v_exp_f32_e32 v80, v80
	v_exp_f32_e32 v81, v81
	v_exp_f32_e32 v82, v82
	v_exp_f32_e32 v83, v83
	v_pk_add_f32 v[84:85], v[84:85], v[188:189]
	v_pk_add_f32 v[86:87], v[86:87], v[188:189]
	v_pk_add_f32 v[80:81], v[80:81], v[188:189]
	v_pk_add_f32 v[82:83], v[82:83], v[188:189]
	v_rcp_f32_e32 v84, v84
	v_rcp_f32_e32 v85, v85
	v_rcp_f32_e32 v86, v86
	v_rcp_f32_e32 v87, v87
	v_rcp_f32_e32 v80, v80
	v_rcp_f32_e32 v81, v81
	v_rcp_f32_e32 v82, v82
	v_rcp_f32_e32 v83, v83
	s_waitcnt vmcnt(24)
	v_permlane16_swap_b32_e32 v240, v242
	v_permlane16_swap_b32_e32 v241, v243
	v_permlane16_swap_b32_e32 v244, v246
	v_permlane16_swap_b32_e32 v245, v247
	v_lshlrev_b32_e32 v168, 16, v240
	v_and_b32_e32 v169, 0xffff0000, v240
	v_lshlrev_b32_e32 v240, 16, v241
	v_and_b32_e32 v241, 0xffff0000, v241
	v_lshlrev_b32_e32 v170, 16, v242
	v_and_b32_e32 v171, 0xffff0000, v242
	v_lshlrev_b32_e32 v242, 16, v243
	v_and_b32_e32 v243, 0xffff0000, v243
	v_lshlrev_b32_e32 v172, 16, v244
	v_and_b32_e32 v173, 0xffff0000, v244
	v_lshlrev_b32_e32 v244, 16, v245
	v_and_b32_e32 v245, 0xffff0000, v245
	v_lshlrev_b32_e32 v174, 16, v246
	v_and_b32_e32 v175, 0xffff0000, v246
	v_lshlrev_b32_e32 v246, 16, v247
	v_and_b32_e32 v247, 0xffff0000, v247
	v_pk_fma_f32 v[84:85], v[84:85], v[172:173], v[168:169]
	v_pk_fma_f32 v[86:87], v[86:87], v[244:245], v[240:241]
	v_pk_fma_f32 v[80:81], v[80:81], v[174:175], v[170:171]
	v_pk_fma_f32 v[82:83], v[82:83], v[246:247], v[242:243]
	v_mov_b32_e32 v172, v80
	v_mov_b32_e32 v173, v81
	v_mov_b32_e32 v174, v82
	v_mov_b32_e32 v175, v83
	v_mov_b32_dpp v80, v84 row_ror:8 row_mask:0xf bank_mask:0x3
	v_mov_b32_dpp v81, v85 row_ror:8 row_mask:0xf bank_mask:0x3
	v_mov_b32_dpp v82, v86 row_ror:8 row_mask:0xf bank_mask:0x3
	v_mov_b32_dpp v83, v87 row_ror:8 row_mask:0xf bank_mask:0x3
	v_mov_b32_dpp v84, v172 row_ror:8 row_mask:0xf bank_mask:0xc
	v_mov_b32_dpp v85, v173 row_ror:8 row_mask:0xf bank_mask:0xc
	v_mov_b32_dpp v86, v174 row_ror:8 row_mask:0xf bank_mask:0xc
	v_mov_b32_dpp v87, v175 row_ror:8 row_mask:0xf bank_mask:0xc
	global_store_dwordx4 v185, v[84:87], s[92:93] offset:512
	global_store_dwordx4 v192, v[80:83], s[92:93] offset:512
	global_load_dwordx4 v[240:243], v182, s[88:89] offset:256
	global_load_dwordx4 v[244:247], v182, s[4:5] offset:256
	v_pk_mul_f32 v[76:77], v[76:77], v[186:187]
	v_pk_mul_f32 v[78:79], v[78:79], v[186:187]
	v_pk_mul_f32 v[72:73], v[72:73], v[186:187]
	v_pk_mul_f32 v[74:75], v[74:75], v[186:187]
	v_exp_f32_e32 v76, v76
	v_exp_f32_e32 v77, v77
	v_exp_f32_e32 v78, v78
	v_exp_f32_e32 v79, v79
	v_exp_f32_e32 v72, v72
	v_exp_f32_e32 v73, v73
	v_exp_f32_e32 v74, v74
	v_exp_f32_e32 v75, v75
	v_pk_add_f32 v[76:77], v[76:77], v[188:189]
	v_pk_add_f32 v[78:79], v[78:79], v[188:189]
	v_pk_add_f32 v[72:73], v[72:73], v[188:189]
	v_pk_add_f32 v[74:75], v[74:75], v[188:189]
	v_rcp_f32_e32 v76, v76
	v_rcp_f32_e32 v77, v77
	v_rcp_f32_e32 v78, v78
	v_rcp_f32_e32 v79, v79
	v_rcp_f32_e32 v72, v72
	v_rcp_f32_e32 v73, v73
	v_rcp_f32_e32 v74, v74
	v_rcp_f32_e32 v75, v75
	s_waitcnt vmcnt(26)
	v_permlane16_swap_b32_e32 v152, v154
	v_permlane16_swap_b32_e32 v153, v155
	v_permlane16_swap_b32_e32 v156, v158
	v_permlane16_swap_b32_e32 v157, v159
	v_lshlrev_b32_e32 v168, 16, v152
	v_and_b32_e32 v169, 0xffff0000, v152
	v_lshlrev_b32_e32 v152, 16, v153
	v_and_b32_e32 v153, 0xffff0000, v153
	v_lshlrev_b32_e32 v170, 16, v154
	v_and_b32_e32 v171, 0xffff0000, v154
	v_lshlrev_b32_e32 v154, 16, v155
	v_and_b32_e32 v155, 0xffff0000, v155
	v_lshlrev_b32_e32 v172, 16, v156
	v_and_b32_e32 v173, 0xffff0000, v156
	v_lshlrev_b32_e32 v156, 16, v157
	v_and_b32_e32 v157, 0xffff0000, v157
	v_lshlrev_b32_e32 v174, 16, v158
	v_and_b32_e32 v175, 0xffff0000, v158
	v_lshlrev_b32_e32 v158, 16, v159
	v_and_b32_e32 v159, 0xffff0000, v159
	v_pk_fma_f32 v[76:77], v[76:77], v[172:173], v[168:169]
	v_pk_fma_f32 v[78:79], v[78:79], v[156:157], v[152:153]
	v_pk_fma_f32 v[72:73], v[72:73], v[174:175], v[170:171]
	v_pk_fma_f32 v[74:75], v[74:75], v[158:159], v[154:155]
	v_add_u32_e32 v185, 0x30000, v184
	v_add_u32_e32 v192, 0x38000, v184
	v_mov_b32_e32 v172, v72
	v_mov_b32_e32 v173, v73
	v_mov_b32_e32 v174, v74
	v_mov_b32_e32 v175, v75
	v_mov_b32_dpp v72, v76 row_ror:8 row_mask:0xf bank_mask:0x3
	v_mov_b32_dpp v73, v77 row_ror:8 row_mask:0xf bank_mask:0x3
	v_mov_b32_dpp v74, v78 row_ror:8 row_mask:0xf bank_mask:0x3
	v_mov_b32_dpp v75, v79 row_ror:8 row_mask:0xf bank_mask:0x3
	v_mov_b32_dpp v76, v172 row_ror:8 row_mask:0xf bank_mask:0xc
	v_mov_b32_dpp v77, v173 row_ror:8 row_mask:0xf bank_mask:0xc
	v_mov_b32_dpp v78, v174 row_ror:8 row_mask:0xf bank_mask:0xc
	v_mov_b32_dpp v79, v175 row_ror:8 row_mask:0xf bank_mask:0xc
	global_store_dwordx4 v185, v[76:79], s[92:93]
	global_store_dwordx4 v192, v[72:75], s[92:93]
	global_load_dwordx4 v[152:155], v183, s[88:89]
	global_load_dwordx4 v[156:159], v183, s[4:5]
	v_pk_mul_f32 v[68:69], v[68:69], v[186:187]
	v_pk_mul_f32 v[70:71], v[70:71], v[186:187]
	v_pk_mul_f32 v[64:65], v[64:65], v[186:187]
	v_pk_mul_f32 v[66:67], v[66:67], v[186:187]
	v_exp_f32_e32 v68, v68
	v_exp_f32_e32 v69, v69
	v_exp_f32_e32 v70, v70
	v_exp_f32_e32 v71, v71
	v_exp_f32_e32 v64, v64
	v_exp_f32_e32 v65, v65
	v_exp_f32_e32 v66, v66
	v_exp_f32_e32 v67, v67
	v_pk_add_f32 v[68:69], v[68:69], v[188:189]
	v_pk_add_f32 v[70:71], v[70:71], v[188:189]
	v_pk_add_f32 v[64:65], v[64:65], v[188:189]
	v_pk_add_f32 v[66:67], v[66:67], v[188:189]
	v_rcp_f32_e32 v68, v68
	v_rcp_f32_e32 v69, v69
	v_rcp_f32_e32 v70, v70
	v_rcp_f32_e32 v71, v71
	v_rcp_f32_e32 v64, v64
	v_rcp_f32_e32 v65, v65
	v_rcp_f32_e32 v66, v66
	v_rcp_f32_e32 v67, v67
	s_waitcnt vmcnt(28)
	v_permlane16_swap_b32_e32 v160, v162
	v_permlane16_swap_b32_e32 v161, v163
	v_permlane16_swap_b32_e32 v164, v166
	v_permlane16_swap_b32_e32 v165, v167
	v_lshlrev_b32_e32 v168, 16, v160
	v_and_b32_e32 v169, 0xffff0000, v160
	v_lshlrev_b32_e32 v160, 16, v161
	v_and_b32_e32 v161, 0xffff0000, v161
	v_lshlrev_b32_e32 v170, 16, v162
	v_and_b32_e32 v171, 0xffff0000, v162
	v_lshlrev_b32_e32 v162, 16, v163
	v_and_b32_e32 v163, 0xffff0000, v163
	v_lshlrev_b32_e32 v172, 16, v164
	v_and_b32_e32 v173, 0xffff0000, v164
	v_lshlrev_b32_e32 v164, 16, v165
	v_and_b32_e32 v165, 0xffff0000, v165
	v_lshlrev_b32_e32 v174, 16, v166
	v_and_b32_e32 v175, 0xffff0000, v166
	v_lshlrev_b32_e32 v166, 16, v167
	v_and_b32_e32 v167, 0xffff0000, v167
	v_pk_fma_f32 v[68:69], v[68:69], v[172:173], v[168:169]
	v_pk_fma_f32 v[70:71], v[70:71], v[164:165], v[160:161]
	v_pk_fma_f32 v[64:65], v[64:65], v[174:175], v[170:171]
	v_pk_fma_f32 v[66:67], v[66:67], v[166:167], v[162:163]
	v_mov_b32_e32 v172, v64
	v_mov_b32_e32 v173, v65
	v_mov_b32_e32 v174, v66
	v_mov_b32_e32 v175, v67
	v_mov_b32_dpp v64, v68 row_ror:8 row_mask:0xf bank_mask:0x3
	v_mov_b32_dpp v65, v69 row_ror:8 row_mask:0xf bank_mask:0x3
	v_mov_b32_dpp v66, v70 row_ror:8 row_mask:0xf bank_mask:0x3
	v_mov_b32_dpp v67, v71 row_ror:8 row_mask:0xf bank_mask:0x3
	v_mov_b32_dpp v68, v172 row_ror:8 row_mask:0xf bank_mask:0xc
	v_mov_b32_dpp v69, v173 row_ror:8 row_mask:0xf bank_mask:0xc
	v_mov_b32_dpp v70, v174 row_ror:8 row_mask:0xf bank_mask:0xc
	v_mov_b32_dpp v71, v175 row_ror:8 row_mask:0xf bank_mask:0xc
	global_store_dwordx4 v185, v[68:71], s[92:93] offset:512
	global_store_dwordx4 v192, v[64:67], s[92:93] offset:512
	global_load_dwordx4 v[160:163], v183, s[88:89] offset:256
	global_load_dwordx4 v[164:167], v183, s[4:5] offset:256
	s_mov_b32 s33, s16
	s_mov_b32 s24, s18
	s_mov_b64 s[28:29], s[22:23]
	s_mov_b64 s[26:27], s[20:21]
	v_pk_mul_f32 v[60:61], v[60:61], v[186:187]
	v_pk_mul_f32 v[62:63], v[62:63], v[186:187]
	v_pk_mul_f32 v[56:57], v[56:57], v[186:187]
	v_pk_mul_f32 v[58:59], v[58:59], v[186:187]
	v_exp_f32_e32 v60, v60
	v_exp_f32_e32 v61, v61
	v_exp_f32_e32 v62, v62
	v_exp_f32_e32 v63, v63
	v_exp_f32_e32 v56, v56
	v_exp_f32_e32 v57, v57
	v_exp_f32_e32 v58, v58
	v_exp_f32_e32 v59, v59
	v_pk_add_f32 v[60:61], v[60:61], v[188:189]
	v_pk_add_f32 v[62:63], v[62:63], v[188:189]
	v_pk_add_f32 v[56:57], v[56:57], v[188:189]
	v_pk_add_f32 v[58:59], v[58:59], v[188:189]
	v_rcp_f32_e32 v60, v60
	v_rcp_f32_e32 v61, v61
	v_rcp_f32_e32 v62, v62
	v_rcp_f32_e32 v63, v63
	v_rcp_f32_e32 v56, v56
	v_rcp_f32_e32 v57, v57
	v_rcp_f32_e32 v58, v58
	v_rcp_f32_e32 v59, v59
	s_waitcnt vmcnt(28)
	v_permlane16_swap_b32_e32 v200, v202
	v_permlane16_swap_b32_e32 v201, v203
	v_permlane16_swap_b32_e32 v204, v206
	v_permlane16_swap_b32_e32 v205, v207
	v_lshlrev_b32_e32 v168, 16, v200
	v_and_b32_e32 v169, 0xffff0000, v200
	v_lshlrev_b32_e32 v200, 16, v201
	v_and_b32_e32 v201, 0xffff0000, v201
	v_lshlrev_b32_e32 v170, 16, v202
	v_and_b32_e32 v171, 0xffff0000, v202
	v_lshlrev_b32_e32 v202, 16, v203
	v_and_b32_e32 v203, 0xffff0000, v203
	v_lshlrev_b32_e32 v172, 16, v204
	v_and_b32_e32 v173, 0xffff0000, v204
	v_lshlrev_b32_e32 v204, 16, v205
	v_and_b32_e32 v205, 0xffff0000, v205
	v_lshlrev_b32_e32 v174, 16, v206
	v_and_b32_e32 v175, 0xffff0000, v206
	v_lshlrev_b32_e32 v206, 16, v207
	v_and_b32_e32 v207, 0xffff0000, v207
	v_pk_fma_f32 v[60:61], v[60:61], v[172:173], v[168:169]
	v_pk_fma_f32 v[62:63], v[62:63], v[204:205], v[200:201]
	v_pk_fma_f32 v[56:57], v[56:57], v[174:175], v[170:171]
	v_pk_fma_f32 v[58:59], v[58:59], v[206:207], v[202:203]
	v_add_u32_e32 v185, 0x80000, v184
	v_add_u32_e32 v192, 0x88000, v184
	v_mov_b32_e32 v172, v56
	v_mov_b32_e32 v173, v57
	v_mov_b32_e32 v174, v58
	v_mov_b32_e32 v175, v59
	v_mov_b32_dpp v56, v60 row_ror:8 row_mask:0xf bank_mask:0x3
	v_mov_b32_dpp v57, v61 row_ror:8 row_mask:0xf bank_mask:0x3
	v_mov_b32_dpp v58, v62 row_ror:8 row_mask:0xf bank_mask:0x3
	v_mov_b32_dpp v59, v63 row_ror:8 row_mask:0xf bank_mask:0x3
	v_mov_b32_dpp v60, v172 row_ror:8 row_mask:0xf bank_mask:0xc
	v_mov_b32_dpp v61, v173 row_ror:8 row_mask:0xf bank_mask:0xc
	v_mov_b32_dpp v62, v174 row_ror:8 row_mask:0xf bank_mask:0xc
	v_mov_b32_dpp v63, v175 row_ror:8 row_mask:0xf bank_mask:0xc
	global_store_dwordx4 v185, v[60:63], s[92:93]
	global_store_dwordx4 v192, v[56:59], s[92:93]
	v_pk_mul_f32 v[52:53], v[52:53], v[186:187]
	v_pk_mul_f32 v[54:55], v[54:55], v[186:187]
	v_pk_mul_f32 v[48:49], v[48:49], v[186:187]
	v_pk_mul_f32 v[50:51], v[50:51], v[186:187]
	v_exp_f32_e32 v52, v52
	v_exp_f32_e32 v53, v53
	v_exp_f32_e32 v54, v54
	v_exp_f32_e32 v55, v55
	v_exp_f32_e32 v48, v48
	v_exp_f32_e32 v49, v49
	v_exp_f32_e32 v50, v50
	v_exp_f32_e32 v51, v51
	v_pk_add_f32 v[52:53], v[52:53], v[188:189]
	v_pk_add_f32 v[54:55], v[54:55], v[188:189]
	v_pk_add_f32 v[48:49], v[48:49], v[188:189]
	v_pk_add_f32 v[50:51], v[50:51], v[188:189]
	v_rcp_f32_e32 v52, v52
	v_rcp_f32_e32 v53, v53
	v_rcp_f32_e32 v54, v54
	v_rcp_f32_e32 v55, v55
	v_rcp_f32_e32 v48, v48
	v_rcp_f32_e32 v49, v49
	v_rcp_f32_e32 v50, v50
	v_rcp_f32_e32 v51, v51
	s_waitcnt vmcnt(26)
	v_permlane16_swap_b32_e32 v208, v210
	v_permlane16_swap_b32_e32 v209, v211
	v_permlane16_swap_b32_e32 v212, v214
	v_permlane16_swap_b32_e32 v213, v215
	v_lshlrev_b32_e32 v168, 16, v208
	v_and_b32_e32 v169, 0xffff0000, v208
	v_lshlrev_b32_e32 v208, 16, v209
	v_and_b32_e32 v209, 0xffff0000, v209
	v_lshlrev_b32_e32 v170, 16, v210
	v_and_b32_e32 v171, 0xffff0000, v210
	v_lshlrev_b32_e32 v210, 16, v211
	v_and_b32_e32 v211, 0xffff0000, v211
	v_lshlrev_b32_e32 v172, 16, v212
	v_and_b32_e32 v173, 0xffff0000, v212
	v_lshlrev_b32_e32 v212, 16, v213
	v_and_b32_e32 v213, 0xffff0000, v213
	v_lshlrev_b32_e32 v174, 16, v214
	v_and_b32_e32 v175, 0xffff0000, v214
	v_lshlrev_b32_e32 v214, 16, v215
	v_and_b32_e32 v215, 0xffff0000, v215
	v_pk_fma_f32 v[52:53], v[52:53], v[172:173], v[168:169]
	v_pk_fma_f32 v[54:55], v[54:55], v[212:213], v[208:209]
	v_pk_fma_f32 v[48:49], v[48:49], v[174:175], v[170:171]
	v_pk_fma_f32 v[50:51], v[50:51], v[214:215], v[210:211]
	v_mov_b32_e32 v172, v48
	v_mov_b32_e32 v173, v49
	v_mov_b32_e32 v174, v50
	v_mov_b32_e32 v175, v51
	v_mov_b32_dpp v48, v52 row_ror:8 row_mask:0xf bank_mask:0x3
	v_mov_b32_dpp v49, v53 row_ror:8 row_mask:0xf bank_mask:0x3
	v_mov_b32_dpp v50, v54 row_ror:8 row_mask:0xf bank_mask:0x3
	v_mov_b32_dpp v51, v55 row_ror:8 row_mask:0xf bank_mask:0x3
	v_mov_b32_dpp v52, v172 row_ror:8 row_mask:0xf bank_mask:0xc
	v_mov_b32_dpp v53, v173 row_ror:8 row_mask:0xf bank_mask:0xc
	v_mov_b32_dpp v54, v174 row_ror:8 row_mask:0xf bank_mask:0xc
	v_mov_b32_dpp v55, v175 row_ror:8 row_mask:0xf bank_mask:0xc
	global_store_dwordx4 v185, v[52:55], s[92:93] offset:512
	global_store_dwordx4 v192, v[48:51], s[92:93] offset:512
	v_pk_mul_f32 v[44:45], v[44:45], v[186:187]
	v_pk_mul_f32 v[46:47], v[46:47], v[186:187]
	v_pk_mul_f32 v[40:41], v[40:41], v[186:187]
	v_pk_mul_f32 v[42:43], v[42:43], v[186:187]
	v_exp_f32_e32 v44, v44
	v_exp_f32_e32 v45, v45
	v_exp_f32_e32 v46, v46
	v_exp_f32_e32 v47, v47
	v_exp_f32_e32 v40, v40
	v_exp_f32_e32 v41, v41
	v_exp_f32_e32 v42, v42
	v_exp_f32_e32 v43, v43
	v_pk_add_f32 v[44:45], v[44:45], v[188:189]
	v_pk_add_f32 v[46:47], v[46:47], v[188:189]
	v_pk_add_f32 v[40:41], v[40:41], v[188:189]
	v_pk_add_f32 v[42:43], v[42:43], v[188:189]
	v_rcp_f32_e32 v44, v44
	v_rcp_f32_e32 v45, v45
	v_rcp_f32_e32 v46, v46
	v_rcp_f32_e32 v47, v47
	v_rcp_f32_e32 v40, v40
	v_rcp_f32_e32 v41, v41
	v_rcp_f32_e32 v42, v42
	v_rcp_f32_e32 v43, v43
	s_waitcnt vmcnt(24)
	v_permlane16_swap_b32_e32 v216, v218
	v_permlane16_swap_b32_e32 v217, v219
	v_permlane16_swap_b32_e32 v220, v222
	v_permlane16_swap_b32_e32 v221, v223
	v_lshlrev_b32_e32 v168, 16, v216
	v_and_b32_e32 v169, 0xffff0000, v216
	v_lshlrev_b32_e32 v216, 16, v217
	v_and_b32_e32 v217, 0xffff0000, v217
	v_lshlrev_b32_e32 v170, 16, v218
	v_and_b32_e32 v171, 0xffff0000, v218
	v_lshlrev_b32_e32 v218, 16, v219
	v_and_b32_e32 v219, 0xffff0000, v219
	v_lshlrev_b32_e32 v172, 16, v220
	v_and_b32_e32 v173, 0xffff0000, v220
	v_lshlrev_b32_e32 v220, 16, v221
	v_and_b32_e32 v221, 0xffff0000, v221
	v_lshlrev_b32_e32 v174, 16, v222
	v_and_b32_e32 v175, 0xffff0000, v222
	v_lshlrev_b32_e32 v222, 16, v223
	v_and_b32_e32 v223, 0xffff0000, v223
	v_pk_fma_f32 v[44:45], v[44:45], v[172:173], v[168:169]
	v_pk_fma_f32 v[46:47], v[46:47], v[220:221], v[216:217]
	v_pk_fma_f32 v[40:41], v[40:41], v[174:175], v[170:171]
	v_pk_fma_f32 v[42:43], v[42:43], v[222:223], v[218:219]
	v_add_u32_e32 v185, 0x90000, v184
	v_add_u32_e32 v192, 0x98000, v184
	v_mov_b32_e32 v172, v40
	v_mov_b32_e32 v173, v41
	v_mov_b32_e32 v174, v42
	v_mov_b32_e32 v175, v43
	v_mov_b32_dpp v40, v44 row_ror:8 row_mask:0xf bank_mask:0x3
	v_mov_b32_dpp v41, v45 row_ror:8 row_mask:0xf bank_mask:0x3
	v_mov_b32_dpp v42, v46 row_ror:8 row_mask:0xf bank_mask:0x3
	v_mov_b32_dpp v43, v47 row_ror:8 row_mask:0xf bank_mask:0x3
	v_mov_b32_dpp v44, v172 row_ror:8 row_mask:0xf bank_mask:0xc
	v_mov_b32_dpp v45, v173 row_ror:8 row_mask:0xf bank_mask:0xc
	v_mov_b32_dpp v46, v174 row_ror:8 row_mask:0xf bank_mask:0xc
	v_mov_b32_dpp v47, v175 row_ror:8 row_mask:0xf bank_mask:0xc
	global_store_dwordx4 v185, v[44:47], s[92:93]
	global_store_dwordx4 v192, v[40:43], s[92:93]
	v_pk_mul_f32 v[36:37], v[36:37], v[186:187]
	v_pk_mul_f32 v[38:39], v[38:39], v[186:187]
	v_pk_mul_f32 v[32:33], v[32:33], v[186:187]
	v_pk_mul_f32 v[34:35], v[34:35], v[186:187]
	v_exp_f32_e32 v36, v36
	v_exp_f32_e32 v37, v37
	v_exp_f32_e32 v38, v38
	v_exp_f32_e32 v39, v39
	v_exp_f32_e32 v32, v32
	v_exp_f32_e32 v33, v33
	v_exp_f32_e32 v34, v34
	v_exp_f32_e32 v35, v35
	v_pk_add_f32 v[36:37], v[36:37], v[188:189]
	v_pk_add_f32 v[38:39], v[38:39], v[188:189]
	v_pk_add_f32 v[32:33], v[32:33], v[188:189]
	v_pk_add_f32 v[34:35], v[34:35], v[188:189]
	v_rcp_f32_e32 v36, v36
	v_rcp_f32_e32 v37, v37
	v_rcp_f32_e32 v38, v38
	v_rcp_f32_e32 v39, v39
	v_rcp_f32_e32 v32, v32
	v_rcp_f32_e32 v33, v33
	v_rcp_f32_e32 v34, v34
	v_rcp_f32_e32 v35, v35
	s_waitcnt vmcnt(22)
	v_permlane16_swap_b32_e32 v224, v226
	v_permlane16_swap_b32_e32 v225, v227
	v_permlane16_swap_b32_e32 v228, v230
	v_permlane16_swap_b32_e32 v229, v231
	v_lshlrev_b32_e32 v168, 16, v224
	v_and_b32_e32 v169, 0xffff0000, v224
	v_lshlrev_b32_e32 v224, 16, v225
	v_and_b32_e32 v225, 0xffff0000, v225
	v_lshlrev_b32_e32 v170, 16, v226
	v_and_b32_e32 v171, 0xffff0000, v226
	v_lshlrev_b32_e32 v226, 16, v227
	v_and_b32_e32 v227, 0xffff0000, v227
	v_lshlrev_b32_e32 v172, 16, v228
	v_and_b32_e32 v173, 0xffff0000, v228
	v_lshlrev_b32_e32 v228, 16, v229
	v_and_b32_e32 v229, 0xffff0000, v229
	v_lshlrev_b32_e32 v174, 16, v230
	v_and_b32_e32 v175, 0xffff0000, v230
	v_lshlrev_b32_e32 v230, 16, v231
	v_and_b32_e32 v231, 0xffff0000, v231
	v_pk_fma_f32 v[36:37], v[36:37], v[172:173], v[168:169]
	v_pk_fma_f32 v[38:39], v[38:39], v[228:229], v[224:225]
	v_pk_fma_f32 v[32:33], v[32:33], v[174:175], v[170:171]
	v_pk_fma_f32 v[34:35], v[34:35], v[230:231], v[226:227]
	v_mov_b32_e32 v172, v32
	v_mov_b32_e32 v173, v33
	v_mov_b32_e32 v174, v34
	v_mov_b32_e32 v175, v35
	v_mov_b32_dpp v32, v36 row_ror:8 row_mask:0xf bank_mask:0x3
	v_mov_b32_dpp v33, v37 row_ror:8 row_mask:0xf bank_mask:0x3
	v_mov_b32_dpp v34, v38 row_ror:8 row_mask:0xf bank_mask:0x3
	v_mov_b32_dpp v35, v39 row_ror:8 row_mask:0xf bank_mask:0x3
	v_mov_b32_dpp v36, v172 row_ror:8 row_mask:0xf bank_mask:0xc
	v_mov_b32_dpp v37, v173 row_ror:8 row_mask:0xf bank_mask:0xc
	v_mov_b32_dpp v38, v174 row_ror:8 row_mask:0xf bank_mask:0xc
	v_mov_b32_dpp v39, v175 row_ror:8 row_mask:0xf bank_mask:0xc
	global_store_dwordx4 v185, v[36:39], s[92:93] offset:512
	global_store_dwordx4 v192, v[32:35], s[92:93] offset:512
	v_pk_mul_f32 v[28:29], v[28:29], v[186:187]
	v_pk_mul_f32 v[30:31], v[30:31], v[186:187]
	v_pk_mul_f32 v[24:25], v[24:25], v[186:187]
	v_pk_mul_f32 v[26:27], v[26:27], v[186:187]
	v_exp_f32_e32 v28, v28
	v_exp_f32_e32 v29, v29
	v_exp_f32_e32 v30, v30
	v_exp_f32_e32 v31, v31
	v_exp_f32_e32 v24, v24
	v_exp_f32_e32 v25, v25
	v_exp_f32_e32 v26, v26
	v_exp_f32_e32 v27, v27
	v_pk_add_f32 v[28:29], v[28:29], v[188:189]
	v_pk_add_f32 v[30:31], v[30:31], v[188:189]
	v_pk_add_f32 v[24:25], v[24:25], v[188:189]
	v_pk_add_f32 v[26:27], v[26:27], v[188:189]
	v_rcp_f32_e32 v28, v28
	v_rcp_f32_e32 v29, v29
	v_rcp_f32_e32 v30, v30
	v_rcp_f32_e32 v31, v31
	v_rcp_f32_e32 v24, v24
	v_rcp_f32_e32 v25, v25
	v_rcp_f32_e32 v26, v26
	v_rcp_f32_e32 v27, v27
	s_waitcnt vmcnt(20)
	v_permlane16_swap_b32_e32 v232, v234
	v_permlane16_swap_b32_e32 v233, v235
	v_permlane16_swap_b32_e32 v236, v238
	v_permlane16_swap_b32_e32 v237, v239
	v_lshlrev_b32_e32 v168, 16, v232
	v_and_b32_e32 v169, 0xffff0000, v232
	v_lshlrev_b32_e32 v232, 16, v233
	v_and_b32_e32 v233, 0xffff0000, v233
	v_lshlrev_b32_e32 v170, 16, v234
	v_and_b32_e32 v171, 0xffff0000, v234
	v_lshlrev_b32_e32 v234, 16, v235
	v_and_b32_e32 v235, 0xffff0000, v235
	v_lshlrev_b32_e32 v172, 16, v236
	v_and_b32_e32 v173, 0xffff0000, v236
	v_lshlrev_b32_e32 v236, 16, v237
	v_and_b32_e32 v237, 0xffff0000, v237
	v_lshlrev_b32_e32 v174, 16, v238
	v_and_b32_e32 v175, 0xffff0000, v238
	v_lshlrev_b32_e32 v238, 16, v239
	v_and_b32_e32 v239, 0xffff0000, v239
	v_pk_fma_f32 v[28:29], v[28:29], v[172:173], v[168:169]
	v_pk_fma_f32 v[30:31], v[30:31], v[236:237], v[232:233]
	v_pk_fma_f32 v[24:25], v[24:25], v[174:175], v[170:171]
	v_pk_fma_f32 v[26:27], v[26:27], v[238:239], v[234:235]
	v_add_u32_e32 v185, 0xa0000, v184
	v_add_u32_e32 v192, 0xa8000, v184
	v_mov_b32_e32 v172, v24
	v_mov_b32_e32 v173, v25
	v_mov_b32_e32 v174, v26
	v_mov_b32_e32 v175, v27
	v_mov_b32_dpp v24, v28 row_ror:8 row_mask:0xf bank_mask:0x3
	v_mov_b32_dpp v25, v29 row_ror:8 row_mask:0xf bank_mask:0x3
	v_mov_b32_dpp v26, v30 row_ror:8 row_mask:0xf bank_mask:0x3
	v_mov_b32_dpp v27, v31 row_ror:8 row_mask:0xf bank_mask:0x3
	v_mov_b32_dpp v28, v172 row_ror:8 row_mask:0xf bank_mask:0xc
	v_mov_b32_dpp v29, v173 row_ror:8 row_mask:0xf bank_mask:0xc
	v_mov_b32_dpp v30, v174 row_ror:8 row_mask:0xf bank_mask:0xc
	v_mov_b32_dpp v31, v175 row_ror:8 row_mask:0xf bank_mask:0xc
	global_store_dwordx4 v185, v[28:31], s[92:93]
	global_store_dwordx4 v192, v[24:27], s[92:93]
	v_pk_mul_f32 v[20:21], v[20:21], v[186:187]
	v_pk_mul_f32 v[22:23], v[22:23], v[186:187]
	v_pk_mul_f32 v[16:17], v[16:17], v[186:187]
	v_pk_mul_f32 v[18:19], v[18:19], v[186:187]
	v_exp_f32_e32 v20, v20
	v_exp_f32_e32 v21, v21
	v_exp_f32_e32 v22, v22
	v_exp_f32_e32 v23, v23
	v_exp_f32_e32 v16, v16
	v_exp_f32_e32 v17, v17
	v_exp_f32_e32 v18, v18
	v_exp_f32_e32 v19, v19
	v_pk_add_f32 v[20:21], v[20:21], v[188:189]
	v_pk_add_f32 v[22:23], v[22:23], v[188:189]
	v_pk_add_f32 v[16:17], v[16:17], v[188:189]
	v_pk_add_f32 v[18:19], v[18:19], v[188:189]
	v_rcp_f32_e32 v20, v20
	v_rcp_f32_e32 v21, v21
	v_rcp_f32_e32 v22, v22
	v_rcp_f32_e32 v23, v23
	v_rcp_f32_e32 v16, v16
	v_rcp_f32_e32 v17, v17
	v_rcp_f32_e32 v18, v18
	v_rcp_f32_e32 v19, v19
	s_waitcnt vmcnt(18)
	v_permlane16_swap_b32_e32 v240, v242
	v_permlane16_swap_b32_e32 v241, v243
	v_permlane16_swap_b32_e32 v244, v246
	v_permlane16_swap_b32_e32 v245, v247
	v_lshlrev_b32_e32 v168, 16, v240
	v_and_b32_e32 v169, 0xffff0000, v240
	v_lshlrev_b32_e32 v240, 16, v241
	v_and_b32_e32 v241, 0xffff0000, v241
	v_lshlrev_b32_e32 v170, 16, v242
	v_and_b32_e32 v171, 0xffff0000, v242
	v_lshlrev_b32_e32 v242, 16, v243
	v_and_b32_e32 v243, 0xffff0000, v243
	v_lshlrev_b32_e32 v172, 16, v244
	v_and_b32_e32 v173, 0xffff0000, v244
	v_lshlrev_b32_e32 v244, 16, v245
	v_and_b32_e32 v245, 0xffff0000, v245
	v_lshlrev_b32_e32 v174, 16, v246
	v_and_b32_e32 v175, 0xffff0000, v246
	v_lshlrev_b32_e32 v246, 16, v247
	v_and_b32_e32 v247, 0xffff0000, v247
	v_pk_fma_f32 v[20:21], v[20:21], v[172:173], v[168:169]
	v_pk_fma_f32 v[22:23], v[22:23], v[244:245], v[240:241]
	v_pk_fma_f32 v[16:17], v[16:17], v[174:175], v[170:171]
	v_pk_fma_f32 v[18:19], v[18:19], v[246:247], v[242:243]
	v_mov_b32_e32 v172, v16
	v_mov_b32_e32 v173, v17
	v_mov_b32_e32 v174, v18
	v_mov_b32_e32 v175, v19
	v_mov_b32_dpp v16, v20 row_ror:8 row_mask:0xf bank_mask:0x3
	v_mov_b32_dpp v17, v21 row_ror:8 row_mask:0xf bank_mask:0x3
	v_mov_b32_dpp v18, v22 row_ror:8 row_mask:0xf bank_mask:0x3
	v_mov_b32_dpp v19, v23 row_ror:8 row_mask:0xf bank_mask:0x3
	v_mov_b32_dpp v20, v172 row_ror:8 row_mask:0xf bank_mask:0xc
	v_mov_b32_dpp v21, v173 row_ror:8 row_mask:0xf bank_mask:0xc
	v_mov_b32_dpp v22, v174 row_ror:8 row_mask:0xf bank_mask:0xc
	v_mov_b32_dpp v23, v175 row_ror:8 row_mask:0xf bank_mask:0xc
	global_store_dwordx4 v185, v[20:23], s[92:93] offset:512
	global_store_dwordx4 v192, v[16:19], s[92:93] offset:512
	v_pk_mul_f32 v[12:13], v[12:13], v[186:187]
	v_pk_mul_f32 v[14:15], v[14:15], v[186:187]
	v_pk_mul_f32 v[8:9], v[8:9], v[186:187]
	v_pk_mul_f32 v[10:11], v[10:11], v[186:187]
	v_exp_f32_e32 v12, v12
	v_exp_f32_e32 v13, v13
	v_exp_f32_e32 v14, v14
	v_exp_f32_e32 v15, v15
	v_exp_f32_e32 v8, v8
	v_exp_f32_e32 v9, v9
	v_exp_f32_e32 v10, v10
	v_exp_f32_e32 v11, v11
	v_pk_add_f32 v[12:13], v[12:13], v[188:189]
	v_pk_add_f32 v[14:15], v[14:15], v[188:189]
	v_pk_add_f32 v[8:9], v[8:9], v[188:189]
	v_pk_add_f32 v[10:11], v[10:11], v[188:189]
	v_rcp_f32_e32 v12, v12
	v_rcp_f32_e32 v13, v13
	v_rcp_f32_e32 v14, v14
	v_rcp_f32_e32 v15, v15
	v_rcp_f32_e32 v8, v8
	v_rcp_f32_e32 v9, v9
	v_rcp_f32_e32 v10, v10
	v_rcp_f32_e32 v11, v11
	s_waitcnt vmcnt(16)
	v_permlane16_swap_b32_e32 v152, v154
	v_permlane16_swap_b32_e32 v153, v155
	v_permlane16_swap_b32_e32 v156, v158
	v_permlane16_swap_b32_e32 v157, v159
	v_lshlrev_b32_e32 v168, 16, v152
	v_and_b32_e32 v169, 0xffff0000, v152
	v_lshlrev_b32_e32 v152, 16, v153
	v_and_b32_e32 v153, 0xffff0000, v153
	v_lshlrev_b32_e32 v170, 16, v154
	v_and_b32_e32 v171, 0xffff0000, v154
	v_lshlrev_b32_e32 v154, 16, v155
	v_and_b32_e32 v155, 0xffff0000, v155
	v_lshlrev_b32_e32 v172, 16, v156
	v_and_b32_e32 v173, 0xffff0000, v156
	v_lshlrev_b32_e32 v156, 16, v157
	v_and_b32_e32 v157, 0xffff0000, v157
	v_lshlrev_b32_e32 v174, 16, v158
	v_and_b32_e32 v175, 0xffff0000, v158
	v_lshlrev_b32_e32 v158, 16, v159
	v_and_b32_e32 v159, 0xffff0000, v159
	v_pk_fma_f32 v[12:13], v[12:13], v[172:173], v[168:169]
	v_pk_fma_f32 v[14:15], v[14:15], v[156:157], v[152:153]
	v_pk_fma_f32 v[8:9], v[8:9], v[174:175], v[170:171]
	v_pk_fma_f32 v[10:11], v[10:11], v[158:159], v[154:155]
	v_add_u32_e32 v185, 0xb0000, v184
	v_add_u32_e32 v192, 0xb8000, v184
	v_mov_b32_e32 v172, v8
	v_mov_b32_e32 v173, v9
	v_mov_b32_e32 v174, v10
	v_mov_b32_e32 v175, v11
	v_mov_b32_dpp v8, v12 row_ror:8 row_mask:0xf bank_mask:0x3
	v_mov_b32_dpp v9, v13 row_ror:8 row_mask:0xf bank_mask:0x3
	v_mov_b32_dpp v10, v14 row_ror:8 row_mask:0xf bank_mask:0x3
	v_mov_b32_dpp v11, v15 row_ror:8 row_mask:0xf bank_mask:0x3
	v_mov_b32_dpp v12, v172 row_ror:8 row_mask:0xf bank_mask:0xc
	v_mov_b32_dpp v13, v173 row_ror:8 row_mask:0xf bank_mask:0xc
	v_mov_b32_dpp v14, v174 row_ror:8 row_mask:0xf bank_mask:0xc
	v_mov_b32_dpp v15, v175 row_ror:8 row_mask:0xf bank_mask:0xc
	global_store_dwordx4 v185, v[12:15], s[92:93]
	global_store_dwordx4 v192, v[8:11], s[92:93]
	v_pk_mul_f32 v[4:5], v[4:5], v[186:187]
	v_pk_mul_f32 v[6:7], v[6:7], v[186:187]
	v_pk_mul_f32 v[0:1], v[0:1], v[186:187]
	v_pk_mul_f32 v[2:3], v[2:3], v[186:187]
	v_exp_f32_e32 v4, v4
	v_exp_f32_e32 v5, v5
	v_exp_f32_e32 v6, v6
	v_exp_f32_e32 v7, v7
	v_exp_f32_e32 v0, v0
	v_exp_f32_e32 v1, v1
	v_exp_f32_e32 v2, v2
	v_exp_f32_e32 v3, v3
	v_pk_add_f32 v[4:5], v[4:5], v[188:189]
	v_pk_add_f32 v[6:7], v[6:7], v[188:189]
	v_pk_add_f32 v[0:1], v[0:1], v[188:189]
	v_pk_add_f32 v[2:3], v[2:3], v[188:189]
	v_rcp_f32_e32 v4, v4
	v_rcp_f32_e32 v5, v5
	v_rcp_f32_e32 v6, v6
	v_rcp_f32_e32 v7, v7
	v_rcp_f32_e32 v0, v0
	v_rcp_f32_e32 v1, v1
	v_rcp_f32_e32 v2, v2
	v_rcp_f32_e32 v3, v3
	s_waitcnt vmcnt(14)
	v_permlane16_swap_b32_e32 v160, v162
	v_permlane16_swap_b32_e32 v161, v163
	v_permlane16_swap_b32_e32 v164, v166
	v_permlane16_swap_b32_e32 v165, v167
	v_lshlrev_b32_e32 v168, 16, v160
	v_and_b32_e32 v169, 0xffff0000, v160
	v_lshlrev_b32_e32 v160, 16, v161
	v_and_b32_e32 v161, 0xffff0000, v161
	v_lshlrev_b32_e32 v170, 16, v162
	v_and_b32_e32 v171, 0xffff0000, v162
	v_lshlrev_b32_e32 v162, 16, v163
	v_and_b32_e32 v163, 0xffff0000, v163
	v_lshlrev_b32_e32 v172, 16, v164
	v_and_b32_e32 v173, 0xffff0000, v164
	v_lshlrev_b32_e32 v164, 16, v165
	v_and_b32_e32 v165, 0xffff0000, v165
	v_lshlrev_b32_e32 v174, 16, v166
	v_and_b32_e32 v175, 0xffff0000, v166
	v_lshlrev_b32_e32 v166, 16, v167
	v_and_b32_e32 v167, 0xffff0000, v167
	v_pk_fma_f32 v[4:5], v[4:5], v[172:173], v[168:169]
	v_pk_fma_f32 v[6:7], v[6:7], v[164:165], v[160:161]
	v_pk_fma_f32 v[0:1], v[0:1], v[174:175], v[170:171]
	v_pk_fma_f32 v[2:3], v[2:3], v[166:167], v[162:163]
	v_mov_b32_e32 v172, v0
	v_mov_b32_e32 v173, v1
	v_mov_b32_e32 v174, v2
	v_mov_b32_e32 v175, v3
	v_mov_b32_dpp v0, v4 row_ror:8 row_mask:0xf bank_mask:0x3
	v_mov_b32_dpp v1, v5 row_ror:8 row_mask:0xf bank_mask:0x3
	v_mov_b32_dpp v2, v6 row_ror:8 row_mask:0xf bank_mask:0x3
	v_mov_b32_dpp v3, v7 row_ror:8 row_mask:0xf bank_mask:0x3
	v_mov_b32_dpp v4, v172 row_ror:8 row_mask:0xf bank_mask:0xc
	v_mov_b32_dpp v5, v173 row_ror:8 row_mask:0xf bank_mask:0xc
	v_mov_b32_dpp v6, v174 row_ror:8 row_mask:0xf bank_mask:0xc
	v_mov_b32_dpp v7, v175 row_ror:8 row_mask:0xf bank_mask:0xc
	global_store_dwordx4 v185, v[4:7], s[92:93] offset:512
	global_store_dwordx4 v192, v[0:3], s[92:93] offset:512
	s_cbranch_vccz .LBB0_1607
	s_waitcnt vmcnt(0)
	s_cmpk_gt_u32 s34, 0xff
	s_cbranch_scc1 .LBB0_1618
	s_barrier
